# v34: P1/P9 next unit's slot-0 LDS-DMA pieces issued inside the SwiGLU epilogue (before its last 2 stores); first-iteration slot-2 wait relaxed to vmcnt(10)
# speedup vs baseline: 1.0030x; 1.0024x over previous
; template <class Epi>
; __device__ __forceinline__ void gemm_phase(LAS unsigned char* lds, const Gemm g, const Sched& S, const Epi& E) {
;     ...
;     for (;;) {
;         const bool has_next = S.next(ui + 1, nxt);
;         const char* nA = has_next ? (const char*)g.A + (size_t)nxt.pm * tstepA + (size_t)nxt.part * g.koff * 2 : cA; const char* nB = has_next ? (const char*)g.Bt + (size_t)nxt.pn * tstepB + (size_t)nxt.part * g.koff * 2 : cB;
.LBB0_575:
	s_mov_b64 s[0:1], 0
	s_mov_b32 s98, 3

; #define PG8_STAGE(bufoff, gbase, voff) do { _Pragma("unroll") for (int _i = 0; _i < 2; ++_i) \
;         __builtin_amdgcn_global_load_lds((const unsigned*)((const char*)(gbase) + (voff)[_i]), (LAS unsigned*)(lds + (bufoff) + ldsw + _i * 8192), 16, 0, 0); } while (0)
; #define PG8_LDA(dst, b, h) do { _Pragma("unroll") for (int m = 0; m < 4; ++m) _Pragma("unroll") for (int k = 0; k < 2; ++k) dst[m][k] = *(const LAS bf16x8*)(lds + PG8_SA(b, h) + aoff + m * 2048 + k * 1024); } while (0)
; #define PG8_LDB(dst, b, h) do { _Pragma("unroll") for (int n = 0; n < 2; ++n) _Pragma("unroll") for (int k = 0; k < 2; ++k) dst[n][k] = *(const LAS bf16x8*)(lds + PG8_SB(b, h) + boff + n * 2048 + k * 1024); } while (0)
; #define PG8_SCHED __builtin_amdgcn_sched_barrier(0)
; template <class Epi>
; __device__ __forceinline__ void gemm_phase(LAS unsigned char* lds, const Gemm g, const Sched& S, const Epi& E) {
;     ...
;             PG8_LDB(B0, 0, 0); PG8_LDB(B1, 0, 1); PG8_SCHED; PG8_LDA(At, 0, 0); PG8_STAGE(PG8_SA(1, 1), a1 + hstepA, voffA);
.LBB0_584:
	ds_read_b128 v[156:159], v153
	ds_read_b128 v[160:163], v153 offset:1024
	ds_read_b128 v[164:167], v153 offset:2048
	ds_read_b128 v[168:171], v153 offset:3072
	ds_read_b128 v[172:175], v154
	ds_read_b128 v[176:179], v154 offset:1024
	ds_read_b128 v[180:183], v154 offset:2048
	ds_read_b128 v[184:187], v154 offset:3072
	s_add_u32 s38, s34, 0xfffc0080
	s_addc_u32 s39, s35, -1
	s_cmp_eq_u32 s86, 12
	s_cselect_b32 s41, s21, s39
	s_cselect_b32 s40, s82, s38
	s_cselect_b32 s39, s19, s85
	s_cselect_b32 s38, s83, s84
	v_lshl_add_u64 v[196:197], s[34:35], 0, v[138:139]
	s_add_i32 m0, s25, 0xc000
	ds_read_b128 v[188:191], v155
	ds_read_b128 v[192:195], v155 offset:1024
	ds_read_b128 v[200:203], v155 offset:2048
	ds_read_b128 v[204:207], v155 offset:3072
	ds_read_b128 v[208:211], v155 offset:4096
	ds_read_b128 v[212:215], v155 offset:5120
	ds_read_b128 v[216:219], v155 offset:6144
	ds_read_b128 v[220:223], v155 offset:7168
	s_cmp_lg_u32 s98, 0
	s_cbranch_scc1 .Lpi_p1_s
	global_load_lds_dwordx4 v[196:197], off
	v_lshl_add_u64 v[196:197], s[34:35], 0, v[140:141]
	s_add_i32 m0, s25, 0xe000
	s_nop 0
	global_load_lds_dwordx4 v[196:197], off
.Lpi_p1_s:
	s_cmp_eq_u32 s98, 0
	s_cbranch_scc1 .Lrx_p1_0_n
	s_sub_u32 s98, s98, 1
	s_waitcnt vmcnt(16)
	s_branch .Lrx_p1_0_j

; #define PG8_STAGE(bufoff, gbase, voff) do { _Pragma("unroll") for (int _i = 0; _i < 2; ++_i) \
;         __builtin_amdgcn_global_load_lds((const unsigned*)((const char*)(gbase) + (voff)[_i]), (LAS unsigned*)(lds + (bufoff) + ldsw + _i * 8192), 16, 0, 0); } while (0)
; #define PG8_LDA(dst, b, h) do { _Pragma("unroll") for (int m = 0; m < 4; ++m) _Pragma("unroll") for (int k = 0; k < 2; ++k) dst[m][k] = *(const LAS bf16x8*)(lds + PG8_SA(b, h) + aoff + m * 2048 + k * 1024); } while (0)
; #define PG8_LDB(dst, b, h) do { _Pragma("unroll") for (int n = 0; n < 2; ++n) _Pragma("unroll") for (int k = 0; k < 2; ++k) dst[n][k] = *(const LAS bf16x8*)(lds + PG8_SB(b, h) + boff + n * 2048 + k * 1024); } while (0)
; #define PG8_SCHED __builtin_amdgcn_sched_barrier(0)
; template <class Epi>
; __device__ __forceinline__ void gemm_phase(LAS unsigned char* lds, const Gemm g, const Sched& S, const Epi& E) {
;     ...
;             PG8_LDB(B0, 1, 0); PG8_LDB(B1, 1, 1); PG8_SCHED; PG8_LDA(At, 1, 0); PG8_STAGE(PG8_SA(0, 1), a2 + hstepA, voffA);
.Lcz_p1_1_j:
	s_setprio 0
	s_barrier
	s_add_i32 s87, 0, 0x18000
	s_add_i32 s88, 0, 0x1c000
	v_add_u32_e32 v168, s87, v147
	v_add_u32_e32 v184, s88, v147
	ds_read_b128 v[156:159], v168
	ds_read_b128 v[160:163], v168 offset:1024
	ds_read_b128 v[164:167], v168 offset:2048
	ds_read_b128 v[168:171], v168 offset:3072
	ds_read_b128 v[172:175], v184
	ds_read_b128 v[176:179], v184 offset:1024
	ds_read_b128 v[180:183], v184 offset:2048
	ds_read_b128 v[184:187], v184 offset:3072
	s_add_u32 s40, s40, 0x40000
	s_addc_u32 s41, s41, 0
	s_mov_b32 m0, s52
	v_lshl_add_u64 v[230:231], s[40:41], 0, v[130:131]
	ds_read_b128 v[188:191], v155 offset:32768
	ds_read_b128 v[192:195], v155 offset:33792
	ds_read_b128 v[200:203], v155 offset:34816
	ds_read_b128 v[204:207], v155 offset:35840
	ds_read_b128 v[208:211], v155 offset:36864
	ds_read_b128 v[212:215], v155 offset:37888
	ds_read_b128 v[216:219], v155 offset:38912
	ds_read_b128 v[220:223], v155 offset:39936
	global_load_lds_dwordx4 v[230:231], off
	v_lshl_add_u64 v[230:231], s[40:41], 0, v[134:135]
	s_mov_b32 m0, s53
	s_nop 0
	global_load_lds_dwordx4 v[230:231], off
	s_cmp_eq_u32 s98, 0
	s_cbranch_scc1 .Lrx_p1_2_n
	s_sub_u32 s98, s98, 1
	s_waitcnt vmcnt(10)
	s_branch .Lrx_p1_2_j

; #define PG8_STAGE(bufoff, gbase, voff) do { _Pragma("unroll") for (int _i = 0; _i < 2; ++_i) \
;         __builtin_amdgcn_global_load_lds((const unsigned*)((const char*)(gbase) + (voff)[_i]), (LAS unsigned*)(lds + (bufoff) + ldsw + _i * 8192), 16, 0, 0); } while (0)
; #define PG8_LDA(dst, b, h) do { _Pragma("unroll") for (int m = 0; m < 4; ++m) _Pragma("unroll") for (int k = 0; k < 2; ++k) dst[m][k] = *(const LAS bf16x8*)(lds + PG8_SA(b, h) + aoff + m * 2048 + k * 1024); } while (0)
; #define PG8_LDB(dst, b, h) do { _Pragma("unroll") for (int n = 0; n < 2; ++n) _Pragma("unroll") for (int k = 0; k < 2; ++k) dst[n][k] = *(const LAS bf16x8*)(lds + PG8_SB(b, h) + boff + n * 2048 + k * 1024); } while (0)
; #define PG8_MMA(ai, bj, At, Bt) do { __builtin_amdgcn_s_setprio(1); _Pragma("unroll") for (int m = 0; m < 4; ++m) _Pragma("unroll") for (int n = 0; n < 2; ++n) _Pragma("unroll") for (int k = 0; k < 2; ++k) \
;         acc[ai][bj][m][n] = __builtin_amdgcn_mfma_f32_16x16x32_bf16(Bt[n][k], At[m][k], acc[ai][bj][m][n], 0, 0, 0); __builtin_amdgcn_s_setprio(0); } while (0)
; #define PG8_WAIT_V(n) asm volatile("s_waitcnt vmcnt(" #n ")" ::: "memory")
; #define PG8_WAIT_L(n) asm volatile("s_waitcnt lgkmcnt(" #n ")" ::: "memory")
; #define PG8_BAR __builtin_amdgcn_s_barrier()
; #define PG8_SCHED __builtin_amdgcn_sched_barrier(0)
; template <class Epi>
; __device__ __forceinline__ void gemm_phase(LAS unsigned char* lds, const Gemm g, const Sched& S, const Epi& E) {
;     ...
;             PG8_LDB(B0, 1, 0); PG8_LDB(B1, 1, 1); PG8_SCHED; PG8_LDA(At, 1, 0); PG8_STAGE(PG8_SA(0, 1), a2 + hstepA, voffA);
;             PG8_WAIT_V(8); PG8_WAIT_L(0); PG8_BAR; PG8_MMA(0, 0, At, B0); PG8_MMA(0, 1, At, B1); PG8_BAR; PG8_SCHED;
;             PG8_LDA(At, 1, 1); PG8_STAGE(PG8_SB(1, 0), b3, voffB); PG8_STAGE(PG8_SB(1, 1), b3 + hstepB, voffB); PG8_STAGE(PG8_SA(1, 0), a3, voffA);
;             PG8_WAIT_V(8); PG8_WAIT_L(0); PG8_BAR; PG8_MMA(1, 0, At, B0); PG8_MMA(1, 1, At, B1); PG8_BAR; PG8_SCHED;
;         }
.Lrx_p1_2_j:
	s_waitcnt lgkmcnt(0)
	s_barrier
	s_setprio 1
	s_waitcnt lgkmcnt(0)
	v_mfma_f32_16x16x32_bf16 v[126:129], v[156:159], v[188:191], v[126:129]
	v_mfma_f32_16x16x32_bf16 v[122:125], v[164:167], v[188:191], v[122:125]
	v_mfma_f32_16x16x32_bf16 v[110:113], v[156:159], v[200:203], v[110:113]
	v_mfma_f32_16x16x32_bf16 v[106:109], v[164:167], v[200:203], v[106:109]
	v_mfma_f32_16x16x32_bf16 v[94:97], v[156:159], v[208:211], v[94:97]
	v_mfma_f32_16x16x32_bf16 v[90:93], v[164:167], v[208:211], v[90:93]
	v_mfma_f32_16x16x32_bf16 v[78:81], v[156:159], v[216:219], v[78:81]
	v_mfma_f32_16x16x32_bf16 v[74:77], v[164:167], v[216:219], v[74:77]
	v_mfma_f32_16x16x32_bf16 v[126:129], v[160:163], v[192:195], v[126:129]
	v_mfma_f32_16x16x32_bf16 v[122:125], v[168:171], v[192:195], v[122:125]
	v_mfma_f32_16x16x32_bf16 v[110:113], v[160:163], v[204:207], v[110:113]
	v_mfma_f32_16x16x32_bf16 v[106:109], v[168:171], v[204:207], v[106:109]
	v_mfma_f32_16x16x32_bf16 v[94:97], v[160:163], v[212:215], v[94:97]
	v_mfma_f32_16x16x32_bf16 v[90:93], v[168:171], v[212:215], v[90:93]
	v_mfma_f32_16x16x32_bf16 v[78:81], v[160:163], v[220:223], v[78:81]
	v_mfma_f32_16x16x32_bf16 v[74:77], v[168:171], v[220:223], v[74:77]
	s_setprio 0
	s_setprio 1
	v_mfma_f32_16x16x32_bf16 v[118:121], v[172:175], v[188:191], v[118:121]
	v_mfma_f32_16x16x32_bf16 v[114:117], v[180:183], v[188:191], v[114:117]
	v_mfma_f32_16x16x32_bf16 v[102:105], v[172:175], v[200:203], v[102:105]
	v_mfma_f32_16x16x32_bf16 v[98:101], v[180:183], v[200:203], v[98:101]
	v_mfma_f32_16x16x32_bf16 v[86:89], v[172:175], v[208:211], v[86:89]
	v_mfma_f32_16x16x32_bf16 v[82:85], v[180:183], v[208:211], v[82:85]
	v_mfma_f32_16x16x32_bf16 v[70:73], v[172:175], v[216:219], v[70:73]
	v_mfma_f32_16x16x32_bf16 v[66:69], v[180:183], v[216:219], v[66:69]
	v_mfma_f32_16x16x32_bf16 v[118:121], v[176:179], v[192:195], v[118:121]
	v_mfma_f32_16x16x32_bf16 v[114:117], v[184:187], v[192:195], v[114:117]
	v_mfma_f32_16x16x32_bf16 v[102:105], v[176:179], v[204:207], v[102:105]
	v_mfma_f32_16x16x32_bf16 v[98:101], v[184:187], v[204:207], v[98:101]
	v_mfma_f32_16x16x32_bf16 v[86:89], v[176:179], v[212:215], v[86:89]
	v_mfma_f32_16x16x32_bf16 v[82:85], v[184:187], v[212:215], v[82:85]
	v_mfma_f32_16x16x32_bf16 v[70:73], v[176:179], v[220:223], v[70:73]
	v_mfma_f32_16x16x32_bf16 v[66:69], v[184:187], v[220:223], v[66:69]
	s_setprio 0
	s_barrier
	s_add_i32 s40, s87, s24
	v_lshl_add_u64 v[196:197], v[196:197], 0, s[6:7]
	s_mov_b32 m0, s40
	ds_read_b128 v[188:191], v155 offset:49152
	ds_read_b128 v[192:195], v155 offset:50176
	ds_read_b128 v[200:203], v155 offset:51200
	ds_read_b128 v[204:207], v155 offset:52224
	ds_read_b128 v[208:211], v155 offset:53248
	ds_read_b128 v[212:215], v155 offset:54272
	ds_read_b128 v[216:219], v155 offset:55296
	ds_read_b128 v[220:223], v155 offset:56320
	global_load_lds_dwordx4 v[196:197], off
	s_add_i32 m0, s40, 0x2000
	s_add_u32 s38, s38, 0x40080
	v_lshl_add_u64 v[196:197], v[224:225], 0, s[6:7]
	s_addc_u32 s39, s39, 0
	s_add_i32 s40, s88, s24
	global_load_lds_dwordx4 v[196:197], off
	v_lshl_add_u64 v[196:197], s[38:39], 0, v[132:133]
	s_mov_b32 m0, s40
	s_nop 0
	global_load_lds_dwordx4 v[196:197], off
	v_lshl_add_u64 v[196:197], s[38:39], 0, v[136:137]
	s_add_i32 m0, s40, 0x2000
	s_nop 0
	global_load_lds_dwordx4 v[196:197], off
	v_lshl_add_u64 v[196:197], v[226:227], 0, s[6:7]
	s_mov_b32 m0, s54
	s_nop 0
	global_load_lds_dwordx4 v[196:197], off
	v_lshl_add_u64 v[196:197], v[228:229], 0, s[6:7]
	s_mov_b32 m0, s55
	s_nop 0
	global_load_lds_dwordx4 v[196:197], off
	s_waitcnt vmcnt(8)
	s_waitcnt lgkmcnt(0)
	s_barrier
	s_setprio 1
	s_waitcnt lgkmcnt(0)
	v_mfma_f32_16x16x32_bf16 v[62:65], v[156:159], v[188:191], v[62:65]
	v_mfma_f32_16x16x32_bf16 v[58:61], v[164:167], v[188:191], v[58:61]
	v_mfma_f32_16x16x32_bf16 v[46:49], v[156:159], v[200:203], v[46:49]
	v_mfma_f32_16x16x32_bf16 v[42:45], v[164:167], v[200:203], v[42:45]
	v_mfma_f32_16x16x32_bf16 v[30:33], v[156:159], v[208:211], v[30:33]
	v_mfma_f32_16x16x32_bf16 v[26:29], v[164:167], v[208:211], v[26:29]
	v_mfma_f32_16x16x32_bf16 v[14:17], v[156:159], v[216:219], v[14:17]
	v_mfma_f32_16x16x32_bf16 v[10:13], v[164:167], v[216:219], v[10:13]
	v_mfma_f32_16x16x32_bf16 v[62:65], v[160:163], v[192:195], v[62:65]
	v_mfma_f32_16x16x32_bf16 v[58:61], v[168:171], v[192:195], v[58:61]
	v_mfma_f32_16x16x32_bf16 v[46:49], v[160:163], v[204:207], v[46:49]
	v_mfma_f32_16x16x32_bf16 v[42:45], v[168:171], v[204:207], v[42:45]
	v_mfma_f32_16x16x32_bf16 v[30:33], v[160:163], v[212:215], v[30:33]
	v_mfma_f32_16x16x32_bf16 v[26:29], v[168:171], v[212:215], v[26:29]
	v_mfma_f32_16x16x32_bf16 v[14:17], v[160:163], v[220:223], v[14:17]
	v_mfma_f32_16x16x32_bf16 v[10:13], v[168:171], v[220:223], v[10:13]
	s_setprio 0
	s_setprio 1
	v_mfma_f32_16x16x32_bf16 v[54:57], v[172:175], v[188:191], v[54:57]
	v_mfma_f32_16x16x32_bf16 v[50:53], v[180:183], v[188:191], v[50:53]
	v_mfma_f32_16x16x32_bf16 v[38:41], v[172:175], v[200:203], v[38:41]
	v_mfma_f32_16x16x32_bf16 v[34:37], v[180:183], v[200:203], v[34:37]
	v_mfma_f32_16x16x32_bf16 v[22:25], v[172:175], v[208:211], v[22:25]
	v_mfma_f32_16x16x32_bf16 v[18:21], v[180:183], v[208:211], v[18:21]
	v_mfma_f32_16x16x32_bf16 v[6:9], v[172:175], v[216:219], v[6:9]
	v_mfma_f32_16x16x32_bf16 v[2:5], v[180:183], v[216:219], v[2:5]
	v_mfma_f32_16x16x32_bf16 v[54:57], v[176:179], v[192:195], v[54:57]
	v_mfma_f32_16x16x32_bf16 v[50:53], v[184:187], v[192:195], v[50:53]
	v_mfma_f32_16x16x32_bf16 v[38:41], v[176:179], v[204:207], v[38:41]
	v_mfma_f32_16x16x32_bf16 v[34:37], v[184:187], v[204:207], v[34:37]
	v_mfma_f32_16x16x32_bf16 v[22:25], v[176:179], v[212:215], v[22:25]
	v_mfma_f32_16x16x32_bf16 v[18:21], v[184:187], v[212:215], v[18:21]
	v_mfma_f32_16x16x32_bf16 v[6:9], v[176:179], v[220:223], v[6:9]
	v_mfma_f32_16x16x32_bf16 v[2:5], v[184:187], v[220:223], v[2:5]
	s_setprio 0
	s_barrier
	s_add_i32 s86, s86, 2
	s_add_u32 s34, s34, 0x100
	s_addc_u32 s35, s35, 0
	s_add_u32 s84, s84, 0x100
	s_addc_u32 s85, s85, 0
	s_cmp_gt_u32 s86, 13
	s_cbranch_scc0 .LBB0_584
	s_and_b64 vcc, exec, s[8:9]
	s_cbranch_vccz .LBB0_587
	s_barrier
; #define LAS __attribute__((address_space(3)))
; __device__ __forceinline__ float siluf_(float x) { return x * sigmoidf_(x); }
; __device__ __forceinline__ u32x4 pack8(const f32x4 a, const f32x4 b) { u32x4 w; w.x = cvtpk(a[0], a[1]); w.y = cvtpk(a[2], a[3]); w.z = cvtpk(b[0], b[1]); w.w = cvtpk(b[2], b[3]); return w; }
;     __device__ __forceinline__ void operator()(const Acc& acc, const Unit& u, int wr, int wc, int fr, int fq) const {
;         const int col0 = u.pn * 128 + wc * 32 + 8 * fq;
;         const LAS float* rt = rtab + u.idx * 256 + wr * 64 + fr;
; #pragma unroll
;         for (int ai = 0; ai < 2; ++ai)
; #pragma unroll
;             for (int m = 0; m < 4; ++m) {
;                 const int row = u.pm * BM + ai * HALF + wr * 64 + m * 16 + fr; const float r = rt[ai * HALF + m * 16];
;                 f32x4 h0, h1;
; #pragma unroll
;                 for (int e = 0; e < 4; ++e) { h0[e] = siluf_(acc[ai][0][m][0][e] * r) * (acc[ai][1][m][0][e] * r); h1[e] = siluf_(acc[ai][0][m][1][e] * r) * (acc[ai][1][m][1][e] * r); }
;                 *(u32x4*)(H + (size_t)row * FF + col0) = pack8(h0, h1);
;             }
.LBB0_587:
	v_lshl_add_u32 v156, s78, 10, v148
	ds_read2_b32 v[158:159], v156 offset1:16
	v_lshl_or_b32 v160, s79, 7, v152
	s_lshl_b32 s19, s30, 8
	v_ashrrev_i32_e32 v161, 31, v160
	s_andn2_b64 vcc, exec, s[0:1]
	s_waitcnt lgkmcnt(0)
	v_pk_mul_f32 v[126:127], v[126:127], v[158:159] op_sel_hi:[1,0]
	v_pk_mul_f32 v[122:123], v[122:123], v[158:159] op_sel_hi:[1,0]
	v_mul_f32_e32 v157, 0xbfb8aa3b, v126
	v_mul_f32_e32 v162, 0xbfb8aa3b, v127
	v_exp_f32_e32 v157, v157
	v_exp_f32_e32 v162, v162
	v_mul_f32_e32 v163, 0xbfb8aa3b, v122
	v_pk_mul_f32 v[118:119], v[118:119], v[158:159] op_sel_hi:[1,0]
	v_add_f32_e32 v157, 1.0, v157
	v_add_f32_e32 v164, 1.0, v162
	v_rcp_f32_e32 v162, v157
	v_exp_f32_e32 v157, v163
	v_mul_f32_e32 v163, 0xbfb8aa3b, v123
	v_exp_f32_e32 v165, v163
	v_rcp_f32_e32 v163, v164
	v_add_f32_e32 v157, 1.0, v157
	v_rcp_f32_e32 v164, v157
	v_add_f32_e32 v157, 1.0, v165
	v_rcp_f32_e32 v165, v157
	v_pk_mul_f32 v[126:127], v[126:127], v[162:163]
	v_pk_mul_f32 v[114:115], v[114:115], v[158:159] op_sel_hi:[1,0]
	v_pk_mul_f32 v[126:127], v[118:119], v[126:127]
	v_pk_mul_f32 v[118:119], v[122:123], v[164:165]
	v_pk_mul_f32 v[122:123], v[128:129], v[158:159] op_sel_hi:[1,0]
	v_pk_mul_f32 v[124:125], v[124:125], v[158:159] op_sel_hi:[1,0]
	v_mul_f32_e32 v128, 0xbfb8aa3b, v122
	v_mul_f32_e32 v129, 0xbfb8aa3b, v123
	v_exp_f32_e32 v128, v128
	v_exp_f32_e32 v129, v129
	v_pk_mul_f32 v[114:115], v[114:115], v[118:119]
	v_pk_mul_f32 v[120:121], v[120:121], v[158:159] op_sel_hi:[1,0]
	v_add_f32_e32 v118, 1.0, v128
	v_add_f32_e32 v119, 1.0, v129
	v_mul_f32_e32 v128, 0xbfb8aa3b, v124
	v_mul_f32_e32 v129, 0xbfb8aa3b, v125
	v_exp_f32_e32 v128, v128
	v_exp_f32_e32 v129, v129
	v_rcp_f32_e32 v118, v118
	v_rcp_f32_e32 v119, v119
	v_add_f32_e32 v128, 1.0, v128
	v_add_f32_e32 v129, 1.0, v129
	v_rcp_f32_e32 v128, v128
	v_rcp_f32_e32 v129, v129
	v_pk_mul_f32 v[118:119], v[122:123], v[118:119]
	v_pk_mul_f32 v[116:117], v[116:117], v[158:159] op_sel_hi:[1,0]
	v_pk_mul_f32 v[122:123], v[120:121], v[118:119]
	v_cvt_pk_bf16_f32 v120, v126, v127
	v_mov_b32_e32 v126, v159
	v_pk_mul_f32 v[110:111], v[110:111], v[126:127] op_sel_hi:[1,0]
	v_pk_mul_f32 v[118:119], v[124:125], v[128:129]
	v_mul_f32_e32 v127, 0xbfb8aa3b, v111
	v_pk_mul_f32 v[116:117], v[116:117], v[118:119]
	v_mul_f32_e32 v119, 0xbfb8aa3b, v110
	v_exp_f32_e32 v127, v127
	v_exp_f32_e32 v119, v119
	v_add_u32_e32 v118, s19, v146
	v_cvt_pk_bf16_f32 v121, v122, v123
	v_cvt_pk_bf16_f32 v122, v114, v115
	v_mov_b64_e32 v[114:115], s[80:81]
	v_cvt_pk_bf16_f32 v123, v116, v117
	v_mad_i64_i32 v[124:125], s[34:35], v118, s74, v[114:115]
	v_lshlrev_b64 v[116:117], 1, v[160:161]
	v_lshl_add_u64 v[124:125], v[124:125], 0, v[116:117]
	v_pk_mul_f32 v[106:107], v[106:107], v[126:127] op_sel_hi:[1,0]
	global_store_dwordx4 v[124:125], v[120:123], off
	v_add_f32_e32 v119, 1.0, v119
	v_pk_mul_f32 v[102:103], v[102:103], v[126:127] op_sel_hi:[1,0]
	v_mul_f32_e32 v121, 0xbfb8aa3b, v106
	v_rcp_f32_e32 v120, v119
	v_add_f32_e32 v119, 1.0, v127
	v_exp_f32_e32 v122, v121
	v_mul_f32_e32 v121, 0xbfb8aa3b, v107
	v_exp_f32_e32 v123, v121
	v_rcp_f32_e32 v121, v119
	v_add_f32_e32 v119, 1.0, v122
	v_rcp_f32_e32 v122, v119
	v_add_f32_e32 v119, 1.0, v123
	v_pk_mul_f32 v[110:111], v[110:111], v[120:121]
	v_rcp_f32_e32 v123, v119
	v_pk_mul_f32 v[102:103], v[102:103], v[110:111]
	v_pk_mul_f32 v[110:111], v[112:113], v[126:127] op_sel_hi:[1,0]
	v_pk_mul_f32 v[98:99], v[98:99], v[126:127] op_sel_hi:[1,0]
	v_mul_f32_e32 v112, 0xbfb8aa3b, v110
	v_mul_f32_e32 v113, 0xbfb8aa3b, v111
	v_exp_f32_e32 v112, v112
	v_exp_f32_e32 v113, v113
	v_pk_mul_f32 v[106:107], v[106:107], v[122:123]
	v_pk_mul_f32 v[108:109], v[108:109], v[126:127] op_sel_hi:[1,0]
	v_pk_mul_f32 v[106:107], v[98:99], v[106:107]
	v_add_f32_e32 v98, 1.0, v112
	v_add_f32_e32 v99, 1.0, v113
	v_mul_f32_e32 v112, 0xbfb8aa3b, v108
	v_mul_f32_e32 v113, 0xbfb8aa3b, v109
	v_exp_f32_e32 v112, v112
	v_exp_f32_e32 v113, v113
	v_rcp_f32_e32 v98, v98
	v_rcp_f32_e32 v99, v99
	v_add_f32_e32 v112, 1.0, v112
	v_add_f32_e32 v113, 1.0, v113
	v_rcp_f32_e32 v112, v112
	v_rcp_f32_e32 v113, v113
	v_pk_mul_f32 v[98:99], v[110:111], v[98:99]
	v_pk_mul_f32 v[104:105], v[104:105], v[126:127] op_sel_hi:[1,0]
	v_pk_mul_f32 v[100:101], v[100:101], v[126:127] op_sel_hi:[1,0]
	v_pk_mul_f32 v[104:105], v[104:105], v[98:99]
	v_pk_mul_f32 v[98:99], v[108:109], v[112:113]
	v_add_u32_e32 v110, s19, v149
	v_pk_mul_f32 v[108:109], v[100:101], v[98:99]
	v_cvt_pk_bf16_f32 v98, v102, v103
	ds_read2_b32 v[102:103], v156 offset0:32 offset1:48
	v_cvt_pk_bf16_f32 v100, v106, v107
	v_cvt_pk_bf16_f32 v99, v104, v105
	v_mad_i64_i32 v[104:105], s[34:35], v110, s74, v[114:115]
	s_waitcnt lgkmcnt(0)
; #define LAS __attribute__((address_space(3)))
; __device__ __forceinline__ float siluf_(float x) { return x * sigmoidf_(x); }
; __device__ __forceinline__ u32x4 pack8(const f32x4 a, const f32x4 b) { u32x4 w; w.x = cvtpk(a[0], a[1]); w.y = cvtpk(a[2], a[3]); w.z = cvtpk(b[0], b[1]); w.w = cvtpk(b[2], b[3]); return w; }
;     __device__ __forceinline__ void operator()(const Acc& acc, const Unit& u, int wr, int wc, int fr, int fq) const {
;         const int col0 = u.pn * 128 + wc * 32 + 8 * fq;
;         const LAS float* rt = rtab + u.idx * 256 + wr * 64 + fr;
; #pragma unroll
;         for (int ai = 0; ai < 2; ++ai)
; #pragma unroll
;             for (int m = 0; m < 4; ++m) {
;                 const int row = u.pm * BM + ai * HALF + wr * 64 + m * 16 + fr; const float r = rt[ai * HALF + m * 16];
;                 f32x4 h0, h1;
; #pragma unroll
;                 for (int e = 0; e < 4; ++e) { h0[e] = siluf_(acc[ai][0][m][0][e] * r) * (acc[ai][1][m][0][e] * r); h1[e] = siluf_(acc[ai][0][m][1][e] * r) * (acc[ai][1][m][1][e] * r); }
;                 *(u32x4*)(H + (size_t)row * FF + col0) = pack8(h0, h1);
;             }
	v_pk_mul_f32 v[94:95], v[94:95], v[102:103] op_sel_hi:[1,0]
	v_cvt_pk_bf16_f32 v101, v108, v109
	v_mul_f32_e32 v106, 0xbfb8aa3b, v94
	v_mul_f32_e32 v107, 0xbfb8aa3b, v95
	v_exp_f32_e32 v106, v106
	v_exp_f32_e32 v107, v107
	v_lshl_add_u64 v[104:105], v[104:105], 0, v[116:117]
	global_store_dwordx4 v[104:105], v[98:101], off
	v_pk_mul_f32 v[90:91], v[90:91], v[102:103] op_sel_hi:[1,0]
	v_pk_mul_f32 v[86:87], v[86:87], v[102:103] op_sel_hi:[1,0]
	v_add_f32_e32 v98, 1.0, v106
	v_add_f32_e32 v99, 1.0, v107
	v_rcp_f32_e32 v98, v98
	v_mul_f32_e32 v100, 0xbfb8aa3b, v90
	v_mul_f32_e32 v101, 0xbfb8aa3b, v91
	v_rcp_f32_e32 v99, v99
	v_exp_f32_e32 v100, v100
	v_exp_f32_e32 v101, v101
	v_pk_mul_f32 v[82:83], v[82:83], v[102:103] op_sel_hi:[1,0]
	v_pk_mul_f32 v[94:95], v[94:95], v[98:99]
	v_add_f32_e32 v100, 1.0, v100
	v_add_f32_e32 v101, 1.0, v101
	v_pk_mul_f32 v[86:87], v[86:87], v[94:95]
	v_pk_mul_f32 v[94:95], v[96:97], v[102:103] op_sel_hi:[1,0]
	v_rcp_f32_e32 v100, v100
	v_rcp_f32_e32 v101, v101
	v_mul_f32_e32 v96, 0xbfb8aa3b, v94
	v_mul_f32_e32 v97, 0xbfb8aa3b, v95
	v_exp_f32_e32 v96, v96
	v_exp_f32_e32 v97, v97
	v_pk_mul_f32 v[90:91], v[90:91], v[100:101]
	v_pk_mul_f32 v[92:93], v[92:93], v[102:103] op_sel_hi:[1,0]
	v_pk_mul_f32 v[90:91], v[82:83], v[90:91]
	v_add_f32_e32 v82, 1.0, v96
	v_add_f32_e32 v83, 1.0, v97
	v_mul_f32_e32 v96, 0xbfb8aa3b, v92
	v_mul_f32_e32 v97, 0xbfb8aa3b, v93
	v_exp_f32_e32 v96, v96
	v_exp_f32_e32 v97, v97
	v_rcp_f32_e32 v82, v82
	v_rcp_f32_e32 v83, v83
	v_add_f32_e32 v96, 1.0, v96
	v_add_f32_e32 v97, 1.0, v97
	v_rcp_f32_e32 v96, v96
	v_rcp_f32_e32 v97, v97
	v_pk_mul_f32 v[82:83], v[94:95], v[82:83]
	v_pk_mul_f32 v[88:89], v[88:89], v[102:103] op_sel_hi:[1,0]
	v_pk_mul_f32 v[84:85], v[84:85], v[102:103] op_sel_hi:[1,0]
	v_pk_mul_f32 v[88:89], v[88:89], v[82:83]
	v_pk_mul_f32 v[82:83], v[92:93], v[96:97]
	v_add_u32_e32 v94, s19, v150
	v_pk_mul_f32 v[92:93], v[84:85], v[82:83]
	v_cvt_pk_bf16_f32 v83, v88, v89
	v_mov_b32_e32 v88, v103
	v_pk_mul_f32 v[78:79], v[78:79], v[88:89] op_sel_hi:[1,0]
	v_cvt_pk_bf16_f32 v84, v90, v91
	v_mul_f32_e32 v89, 0xbfb8aa3b, v78
	v_mul_f32_e32 v90, 0xbfb8aa3b, v79
	v_exp_f32_e32 v89, v89
	v_exp_f32_e32 v90, v90
	v_cvt_pk_bf16_f32 v82, v86, v87
	v_mad_i64_i32 v[86:87], s[34:35], v94, s74, v[114:115]
	v_cvt_pk_bf16_f32 v85, v92, v93
	v_lshl_add_u64 v[86:87], v[86:87], 0, v[116:117]
	global_store_dwordx4 v[86:87], v[82:85], off
	v_pk_mul_f32 v[74:75], v[74:75], v[88:89] op_sel_hi:[1,0]
	v_pk_mul_f32 v[70:71], v[70:71], v[88:89] op_sel_hi:[1,0]
	v_add_f32_e32 v82, 1.0, v89
	v_add_f32_e32 v83, 1.0, v90
	v_rcp_f32_e32 v82, v82
	v_mul_f32_e32 v84, 0xbfb8aa3b, v74
	v_mul_f32_e32 v85, 0xbfb8aa3b, v75
	v_rcp_f32_e32 v83, v83
	v_exp_f32_e32 v84, v84
	v_exp_f32_e32 v85, v85
	v_pk_mul_f32 v[66:67], v[66:67], v[88:89] op_sel_hi:[1,0]
	v_pk_mul_f32 v[78:79], v[78:79], v[82:83]
	v_add_f32_e32 v84, 1.0, v84
	v_add_f32_e32 v85, 1.0, v85
	v_pk_mul_f32 v[70:71], v[70:71], v[78:79]
	v_pk_mul_f32 v[78:79], v[80:81], v[88:89] op_sel_hi:[1,0]
	v_rcp_f32_e32 v84, v84
	v_rcp_f32_e32 v85, v85
	v_mul_f32_e32 v80, 0xbfb8aa3b, v78
	v_mul_f32_e32 v81, 0xbfb8aa3b, v79
	v_exp_f32_e32 v80, v80
	v_exp_f32_e32 v81, v81
	v_pk_mul_f32 v[74:75], v[74:75], v[84:85]
	v_pk_mul_f32 v[76:77], v[76:77], v[88:89] op_sel_hi:[1,0]
	v_pk_mul_f32 v[74:75], v[66:67], v[74:75]
	v_add_f32_e32 v66, 1.0, v80
	v_add_f32_e32 v67, 1.0, v81
	v_mul_f32_e32 v80, 0xbfb8aa3b, v76
	v_mul_f32_e32 v81, 0xbfb8aa3b, v77
	v_exp_f32_e32 v80, v80
	v_exp_f32_e32 v81, v81
	v_rcp_f32_e32 v66, v66
	v_rcp_f32_e32 v67, v67
	v_add_f32_e32 v80, 1.0, v80
	v_add_f32_e32 v81, 1.0, v81
	v_rcp_f32_e32 v80, v80
	v_rcp_f32_e32 v81, v81
	v_pk_mul_f32 v[66:67], v[78:79], v[66:67]
	v_pk_mul_f32 v[72:73], v[72:73], v[88:89] op_sel_hi:[1,0]
	v_pk_mul_f32 v[68:69], v[68:69], v[88:89] op_sel_hi:[1,0]
	v_pk_mul_f32 v[72:73], v[72:73], v[66:67]
	v_pk_mul_f32 v[66:67], v[76:77], v[80:81]
	v_add_u32_e32 v78, s19, v151
	v_pk_mul_f32 v[76:77], v[68:69], v[66:67]
	v_cvt_pk_bf16_f32 v66, v70, v71
	ds_read2_b32 v[70:71], v156 offset0:128 offset1:144
	v_cvt_pk_bf16_f32 v68, v74, v75
	v_cvt_pk_bf16_f32 v67, v72, v73
	v_mad_i64_i32 v[72:73], s[34:35], v78, s74, v[114:115]
	s_waitcnt lgkmcnt(0)
	v_pk_mul_f32 v[62:63], v[62:63], v[70:71] op_sel_hi:[1,0]
	v_cvt_pk_bf16_f32 v69, v76, v77
	v_mul_f32_e32 v74, 0xbfb8aa3b, v62
	v_mul_f32_e32 v75, 0xbfb8aa3b, v63
	v_exp_f32_e32 v74, v74
	v_exp_f32_e32 v75, v75
	v_lshl_add_u64 v[72:73], v[72:73], 0, v[116:117]
	global_store_dwordx4 v[72:73], v[66:69], off
	v_pk_mul_f32 v[58:59], v[58:59], v[70:71] op_sel_hi:[1,0]
	v_pk_mul_f32 v[54:55], v[54:55], v[70:71] op_sel_hi:[1,0]
	v_add_f32_e32 v66, 1.0, v74
	v_add_f32_e32 v67, 1.0, v75
	v_rcp_f32_e32 v66, v66
	v_mul_f32_e32 v68, 0xbfb8aa3b, v58
	v_mul_f32_e32 v69, 0xbfb8aa3b, v59
	v_rcp_f32_e32 v67, v67
	v_exp_f32_e32 v68, v68
	v_exp_f32_e32 v69, v69
	v_pk_mul_f32 v[50:51], v[50:51], v[70:71] op_sel_hi:[1,0]
	v_pk_mul_f32 v[62:63], v[62:63], v[66:67]
	v_add_f32_e32 v68, 1.0, v68
	v_add_f32_e32 v69, 1.0, v69
	v_pk_mul_f32 v[54:55], v[54:55], v[62:63]
	v_pk_mul_f32 v[62:63], v[64:65], v[70:71] op_sel_hi:[1,0]
	v_rcp_f32_e32 v68, v68
	v_rcp_f32_e32 v69, v69
	v_mul_f32_e32 v64, 0xbfb8aa3b, v62
	v_mul_f32_e32 v65, 0xbfb8aa3b, v63
	v_exp_f32_e32 v64, v64
	v_exp_f32_e32 v65, v65
	v_pk_mul_f32 v[58:59], v[58:59], v[68:69]
	v_pk_mul_f32 v[60:61], v[60:61], v[70:71] op_sel_hi:[1,0]
	v_pk_mul_f32 v[58:59], v[50:51], v[58:59]
	v_add_f32_e32 v50, 1.0, v64
	v_add_f32_e32 v51, 1.0, v65
	v_mul_f32_e32 v64, 0xbfb8aa3b, v60
	v_mul_f32_e32 v65, 0xbfb8aa3b, v61
	v_exp_f32_e32 v64, v64
	v_exp_f32_e32 v65, v65
	v_rcp_f32_e32 v50, v50
; #define LAS __attribute__((address_space(3)))
; __device__ __forceinline__ float siluf_(float x) { return x * sigmoidf_(x); }
; __device__ __forceinline__ u32x4 pack8(const f32x4 a, const f32x4 b) { u32x4 w; w.x = cvtpk(a[0], a[1]); w.y = cvtpk(a[2], a[3]); w.z = cvtpk(b[0], b[1]); w.w = cvtpk(b[2], b[3]); return w; }
;     __device__ __forceinline__ void operator()(const Acc& acc, const Unit& u, int wr, int wc, int fr, int fq) const {
;         const int col0 = u.pn * 128 + wc * 32 + 8 * fq;
;         const LAS float* rt = rtab + u.idx * 256 + wr * 64 + fr;
; #pragma unroll
;         for (int ai = 0; ai < 2; ++ai)
; #pragma unroll
;             for (int m = 0; m < 4; ++m) {
;                 const int row = u.pm * BM + ai * HALF + wr * 64 + m * 16 + fr; const float r = rt[ai * HALF + m * 16];
;                 f32x4 h0, h1;
; #pragma unroll
;                 for (int e = 0; e < 4; ++e) { h0[e] = siluf_(acc[ai][0][m][0][e] * r) * (acc[ai][1][m][0][e] * r); h1[e] = siluf_(acc[ai][0][m][1][e] * r) * (acc[ai][1][m][1][e] * r); }
;                 *(u32x4*)(H + (size_t)row * FF + col0) = pack8(h0, h1);
;             }
	v_rcp_f32_e32 v51, v51
	v_add_f32_e32 v64, 1.0, v64
	v_add_f32_e32 v65, 1.0, v65
	v_rcp_f32_e32 v64, v64
	v_rcp_f32_e32 v65, v65
	v_pk_mul_f32 v[50:51], v[62:63], v[50:51]
	v_pk_mul_f32 v[56:57], v[56:57], v[70:71] op_sel_hi:[1,0]
	v_pk_mul_f32 v[52:53], v[52:53], v[70:71] op_sel_hi:[1,0]
	v_pk_mul_f32 v[56:57], v[56:57], v[50:51]
	v_pk_mul_f32 v[50:51], v[60:61], v[64:65]
	v_add_u32_e32 v62, 0x80, v118
	v_pk_mul_f32 v[60:61], v[52:53], v[50:51]
	v_cvt_pk_bf16_f32 v51, v56, v57
	v_mov_b32_e32 v56, v71
	v_pk_mul_f32 v[46:47], v[46:47], v[56:57] op_sel_hi:[1,0]
	v_cvt_pk_bf16_f32 v52, v58, v59
	v_mul_f32_e32 v57, 0xbfb8aa3b, v46
	v_mul_f32_e32 v58, 0xbfb8aa3b, v47
	v_exp_f32_e32 v57, v57
	v_exp_f32_e32 v58, v58
	v_cvt_pk_bf16_f32 v50, v54, v55
	v_mad_i64_i32 v[54:55], s[34:35], v62, s74, v[114:115]
	v_cvt_pk_bf16_f32 v53, v60, v61
	v_lshl_add_u64 v[54:55], v[54:55], 0, v[116:117]
	global_store_dwordx4 v[54:55], v[50:53], off
	v_pk_mul_f32 v[42:43], v[42:43], v[56:57] op_sel_hi:[1,0]
	v_pk_mul_f32 v[38:39], v[38:39], v[56:57] op_sel_hi:[1,0]
	v_add_f32_e32 v50, 1.0, v57
	v_add_f32_e32 v51, 1.0, v58
	v_rcp_f32_e32 v50, v50
	v_mul_f32_e32 v52, 0xbfb8aa3b, v42
	v_mul_f32_e32 v53, 0xbfb8aa3b, v43
	v_rcp_f32_e32 v51, v51
	v_exp_f32_e32 v52, v52
	v_exp_f32_e32 v53, v53
	v_pk_mul_f32 v[34:35], v[34:35], v[56:57] op_sel_hi:[1,0]
	v_pk_mul_f32 v[46:47], v[46:47], v[50:51]
	v_add_f32_e32 v52, 1.0, v52
	v_add_f32_e32 v53, 1.0, v53
	v_pk_mul_f32 v[38:39], v[38:39], v[46:47]
	v_pk_mul_f32 v[46:47], v[48:49], v[56:57] op_sel_hi:[1,0]
	v_rcp_f32_e32 v52, v52
	v_rcp_f32_e32 v53, v53
	v_mul_f32_e32 v48, 0xbfb8aa3b, v46
	v_mul_f32_e32 v49, 0xbfb8aa3b, v47
	v_exp_f32_e32 v48, v48
	v_exp_f32_e32 v49, v49
	v_pk_mul_f32 v[42:43], v[42:43], v[52:53]
	v_pk_mul_f32 v[44:45], v[44:45], v[56:57] op_sel_hi:[1,0]
	v_pk_mul_f32 v[42:43], v[34:35], v[42:43]
	v_add_f32_e32 v34, 1.0, v48
	v_add_f32_e32 v35, 1.0, v49
	v_mul_f32_e32 v48, 0xbfb8aa3b, v44
	v_mul_f32_e32 v49, 0xbfb8aa3b, v45
	v_exp_f32_e32 v48, v48
	v_exp_f32_e32 v49, v49
	v_rcp_f32_e32 v34, v34
	v_rcp_f32_e32 v35, v35
	v_add_f32_e32 v48, 1.0, v48
	v_add_f32_e32 v49, 1.0, v49
	v_rcp_f32_e32 v48, v48
	v_rcp_f32_e32 v49, v49
	v_pk_mul_f32 v[34:35], v[46:47], v[34:35]
	v_pk_mul_f32 v[40:41], v[40:41], v[56:57] op_sel_hi:[1,0]
	v_pk_mul_f32 v[36:37], v[36:37], v[56:57] op_sel_hi:[1,0]
	v_pk_mul_f32 v[40:41], v[40:41], v[34:35]
	v_pk_mul_f32 v[34:35], v[44:45], v[48:49]
	v_add_u32_e32 v46, 0x90, v118
	v_pk_mul_f32 v[44:45], v[36:37], v[34:35]
	v_cvt_pk_bf16_f32 v34, v38, v39
	ds_read2_b32 v[38:39], v156 offset0:160 offset1:176
	v_cvt_pk_bf16_f32 v36, v42, v43
	v_cvt_pk_bf16_f32 v35, v40, v41
	v_mad_i64_i32 v[40:41], s[34:35], v46, s74, v[114:115]
	s_waitcnt lgkmcnt(0)
	v_pk_mul_f32 v[30:31], v[30:31], v[38:39] op_sel_hi:[1,0]
	v_cvt_pk_bf16_f32 v37, v44, v45
	v_mul_f32_e32 v42, 0xbfb8aa3b, v30
	v_mul_f32_e32 v43, 0xbfb8aa3b, v31
	v_exp_f32_e32 v42, v42
	v_exp_f32_e32 v43, v43
	v_lshl_add_u64 v[40:41], v[40:41], 0, v[116:117]
	global_store_dwordx4 v[40:41], v[34:37], off
	s_cbranch_vccnz .Lpi_p1_e
	s_add_u32 s100, s22, 0x40080
	s_addc_u32 s101, s23, 0
	v_lshl_add_u64 v[196:197], s[100:101], 0, v[138:139]
	s_add_i32 m0, s25, 0xc000
	s_nop 0
	global_load_lds_dwordx4 v[196:197], off
	v_lshl_add_u64 v[196:197], s[100:101], 0, v[140:141]
	s_add_i32 m0, s25, 0xe000
	s_nop 0
	global_load_lds_dwordx4 v[196:197], off
; #define LAS __attribute__((address_space(3)))
; __device__ __forceinline__ float siluf_(float x) { return x * sigmoidf_(x); }
; #define PG8_BAR __builtin_amdgcn_s_barrier()
; __device__ __forceinline__ u32x4 pack8(const f32x4 a, const f32x4 b) { u32x4 w; w.x = cvtpk(a[0], a[1]); w.y = cvtpk(a[2], a[3]); w.z = cvtpk(b[0], b[1]); w.w = cvtpk(b[2], b[3]); return w; }
; template <class Epi>
; __device__ __forceinline__ void gemm_phase(LAS unsigned char* lds, const Gemm g, const Sched& S, const Epi& E) {
;     ...
;         if (!has_next) break;
;         if (!(Epi::KEEP_PART0 && cur.part == 0))
; #pragma unroll
;         for (int a = 0; a < 2; ++a)
; #pragma unroll
;             for (int b = 0; b < 2; ++b)
; #pragma unroll
;                 for (int m = 0; m < 4; ++m)
; #pragma unroll
;                     for (int n = 0; n < 2; ++n) acc[a][b][m][n] = (f32x4){0.f, 0.f, 0.f, 0.f};
;         cur = nxt; cA = nA; cB = nB; ++ui;
;         if (wr == 1) PG8_BAR;
;     __device__ __forceinline__ void operator()(const Acc& acc, const Unit& u, int wr, int wc, int fr, int fq) const {
;         const int col0 = u.pn * 128 + wc * 32 + 8 * fq;
;         const LAS float* rt = rtab + u.idx * 256 + wr * 64 + fr;
; #pragma unroll
;         for (int ai = 0; ai < 2; ++ai)
; #pragma unroll
;             for (int m = 0; m < 4; ++m) {
;                 const int row = u.pm * BM + ai * HALF + wr * 64 + m * 16 + fr; const float r = rt[ai * HALF + m * 16];
;                 f32x4 h0, h1;
; #pragma unroll
;                 for (int e = 0; e < 4; ++e) { h0[e] = siluf_(acc[ai][0][m][0][e] * r) * (acc[ai][1][m][0][e] * r); h1[e] = siluf_(acc[ai][0][m][1][e] * r) * (acc[ai][1][m][1][e] * r); }
;                 *(u32x4*)(H + (size_t)row * FF + col0) = pack8(h0, h1);
;             }
.Lpi_p1_e:
	v_pk_mul_f32 v[26:27], v[26:27], v[38:39] op_sel_hi:[1,0]
	v_pk_mul_f32 v[22:23], v[22:23], v[38:39] op_sel_hi:[1,0]
	v_add_f32_e32 v34, 1.0, v42
	v_add_f32_e32 v35, 1.0, v43
	v_rcp_f32_e32 v34, v34
	v_mul_f32_e32 v36, 0xbfb8aa3b, v26
	v_mul_f32_e32 v37, 0xbfb8aa3b, v27
	v_rcp_f32_e32 v35, v35
	v_exp_f32_e32 v36, v36
	v_exp_f32_e32 v37, v37
	v_pk_mul_f32 v[18:19], v[18:19], v[38:39] op_sel_hi:[1,0]
	v_pk_mul_f32 v[30:31], v[30:31], v[34:35]
	v_add_f32_e32 v36, 1.0, v36
	v_add_f32_e32 v37, 1.0, v37
	v_pk_mul_f32 v[22:23], v[22:23], v[30:31]
	v_pk_mul_f32 v[30:31], v[32:33], v[38:39] op_sel_hi:[1,0]
	v_rcp_f32_e32 v36, v36
	v_rcp_f32_e32 v37, v37
	v_mul_f32_e32 v32, 0xbfb8aa3b, v30
	v_mul_f32_e32 v33, 0xbfb8aa3b, v31
	v_exp_f32_e32 v32, v32
	v_exp_f32_e32 v33, v33
	v_pk_mul_f32 v[26:27], v[26:27], v[36:37]
	v_pk_mul_f32 v[28:29], v[28:29], v[38:39] op_sel_hi:[1,0]
	v_pk_mul_f32 v[26:27], v[18:19], v[26:27]
	v_add_f32_e32 v18, 1.0, v32
	v_add_f32_e32 v19, 1.0, v33
	v_mul_f32_e32 v32, 0xbfb8aa3b, v28
	v_mul_f32_e32 v33, 0xbfb8aa3b, v29
	v_exp_f32_e32 v32, v32
	v_exp_f32_e32 v33, v33
	v_rcp_f32_e32 v18, v18
	v_rcp_f32_e32 v19, v19
	v_add_f32_e32 v32, 1.0, v32
	v_add_f32_e32 v33, 1.0, v33
	v_rcp_f32_e32 v32, v32
	v_rcp_f32_e32 v33, v33
	v_pk_mul_f32 v[18:19], v[30:31], v[18:19]
	v_pk_mul_f32 v[24:25], v[24:25], v[38:39] op_sel_hi:[1,0]
	v_pk_mul_f32 v[20:21], v[20:21], v[38:39] op_sel_hi:[1,0]
	v_pk_mul_f32 v[24:25], v[24:25], v[18:19]
	v_pk_mul_f32 v[18:19], v[28:29], v[32:33]
	v_add_u32_e32 v30, 0xa0, v118
	v_pk_mul_f32 v[28:29], v[20:21], v[18:19]
	v_cvt_pk_bf16_f32 v19, v24, v25
	v_mov_b32_e32 v24, v39
	v_pk_mul_f32 v[14:15], v[14:15], v[24:25] op_sel_hi:[1,0]
	v_cvt_pk_bf16_f32 v20, v26, v27
	v_mul_f32_e32 v25, 0xbfb8aa3b, v14
	v_mul_f32_e32 v26, 0xbfb8aa3b, v15
	v_exp_f32_e32 v25, v25
	v_exp_f32_e32 v26, v26
	v_cvt_pk_bf16_f32 v18, v22, v23
	v_mad_i64_i32 v[22:23], s[34:35], v30, s74, v[114:115]
	v_cvt_pk_bf16_f32 v21, v28, v29
	v_lshl_add_u64 v[22:23], v[22:23], 0, v[116:117]
	global_store_dwordx4 v[22:23], v[18:21], off
	v_pk_mul_f32 v[10:11], v[10:11], v[24:25] op_sel_hi:[1,0]
	v_pk_mul_f32 v[6:7], v[6:7], v[24:25] op_sel_hi:[1,0]
	v_add_f32_e32 v18, 1.0, v25
	v_add_f32_e32 v19, 1.0, v26
	v_rcp_f32_e32 v18, v18
	v_mul_f32_e32 v20, 0xbfb8aa3b, v10
	v_mul_f32_e32 v21, 0xbfb8aa3b, v11
	v_rcp_f32_e32 v19, v19
	v_exp_f32_e32 v20, v20
	v_exp_f32_e32 v21, v21
	v_pk_mul_f32 v[2:3], v[2:3], v[24:25] op_sel_hi:[1,0]
	v_pk_mul_f32 v[14:15], v[14:15], v[18:19]
	v_add_f32_e32 v20, 1.0, v20
	v_add_f32_e32 v21, 1.0, v21
	v_pk_mul_f32 v[6:7], v[6:7], v[14:15]
	v_pk_mul_f32 v[14:15], v[16:17], v[24:25] op_sel_hi:[1,0]
	v_rcp_f32_e32 v20, v20
	v_rcp_f32_e32 v21, v21
	v_mul_f32_e32 v16, 0xbfb8aa3b, v14
	v_mul_f32_e32 v17, 0xbfb8aa3b, v15
	v_exp_f32_e32 v16, v16
	v_exp_f32_e32 v17, v17
	v_pk_mul_f32 v[10:11], v[10:11], v[20:21]
	v_pk_mul_f32 v[12:13], v[12:13], v[24:25] op_sel_hi:[1,0]
	v_pk_mul_f32 v[10:11], v[2:3], v[10:11]
	v_add_f32_e32 v2, 1.0, v16
	v_add_f32_e32 v3, 1.0, v17
	v_mul_f32_e32 v16, 0xbfb8aa3b, v12
	v_mul_f32_e32 v17, 0xbfb8aa3b, v13
	v_exp_f32_e32 v16, v16
	v_exp_f32_e32 v17, v17
	v_rcp_f32_e32 v2, v2
	v_rcp_f32_e32 v3, v3
	v_add_f32_e32 v16, 1.0, v16
	v_add_f32_e32 v17, 1.0, v17
	v_rcp_f32_e32 v16, v16
	v_rcp_f32_e32 v17, v17
	v_pk_mul_f32 v[2:3], v[14:15], v[2:3]
	v_pk_mul_f32 v[8:9], v[8:9], v[24:25] op_sel_hi:[1,0]
	v_pk_mul_f32 v[4:5], v[4:5], v[24:25] op_sel_hi:[1,0]
	v_pk_mul_f32 v[8:9], v[8:9], v[2:3]
	v_pk_mul_f32 v[2:3], v[12:13], v[16:17]
	v_add_u32_e32 v14, 0xb0, v118
	v_pk_mul_f32 v[12:13], v[4:5], v[2:3]
	v_cvt_pk_bf16_f32 v2, v6, v7
	v_mad_i64_i32 v[6:7], s[34:35], v14, s74, v[114:115]
	v_cvt_pk_bf16_f32 v3, v8, v9
	v_cvt_pk_bf16_f32 v4, v10, v11
	v_cvt_pk_bf16_f32 v5, v12, v13
	v_lshl_add_u64 v[6:7], v[6:7], 0, v[116:117]
	s_mov_b64 s[0:1], -1
	global_store_dwordx4 v[6:7], v[2:5], off
	s_cbranch_vccnz .LBB0_576
	s_andn2_b64 vcc, exec, s[4:5]
	s_cbranch_vccnz .LBB0_575
	s_barrier
	s_branch .LBB0_575

; #define PG8_STAGE(bufoff, gbase, voff) do { _Pragma("unroll") for (int _i = 0; _i < 2; ++_i) \
;         __builtin_amdgcn_global_load_lds((const unsigned*)((const char*)(gbase) + (voff)[_i]), (LAS unsigned*)(lds + (bufoff) + ldsw + _i * 8192), 16, 0, 0); } while (0)
; #define PG8_LDA(dst, b, h) do { _Pragma("unroll") for (int m = 0; m < 4; ++m) _Pragma("unroll") for (int k = 0; k < 2; ++k) dst[m][k] = *(const LAS bf16x8*)(lds + PG8_SA(b, h) + aoff + m * 2048 + k * 1024); } while (0)
; #define PG8_LDB(dst, b, h) do { _Pragma("unroll") for (int n = 0; n < 2; ++n) _Pragma("unroll") for (int k = 0; k < 2; ++k) dst[n][k] = *(const LAS bf16x8*)(lds + PG8_SB(b, h) + boff + n * 2048 + k * 1024); } while (0)
; #define PG8_SCHED __builtin_amdgcn_sched_barrier(0)
; template <class Epi>
; __device__ __forceinline__ void gemm_phase(LAS unsigned char* lds, const Gemm g, const Sched& S, const Epi& E) {
;     ...
;             PG8_LDB(B0, 0, 0); PG8_LDB(B1, 0, 1); PG8_SCHED; PG8_LDA(At, 0, 0); PG8_STAGE(PG8_SA(1, 1), a1 + hstepA, voffA);
.LBB0_1718:
	ds_read_b128 v[156:159], v153
	ds_read_b128 v[160:163], v153 offset:1024
	ds_read_b128 v[164:167], v153 offset:2048
	ds_read_b128 v[168:171], v153 offset:3072
	ds_read_b128 v[172:175], v154
	ds_read_b128 v[176:179], v154 offset:1024
	ds_read_b128 v[180:183], v154 offset:2048
	ds_read_b128 v[184:187], v154 offset:3072
	s_add_u32 s24, s22, 0xfffc0080
	s_addc_u32 s25, s23, -1
	s_cmp_eq_u32 s53, 12
	s_cselect_b32 s27, s15, s25
	s_cselect_b32 s26, s45, s24
	s_cselect_b32 s25, s11, s52
	s_cselect_b32 s24, s46, s47
	v_lshl_add_u64 v[196:197], s[22:23], 0, v[138:139]
	s_add_i32 m0, s21, 0xc000
	ds_read_b128 v[188:191], v155
	ds_read_b128 v[192:195], v155 offset:1024
	ds_read_b128 v[200:203], v155 offset:2048
	ds_read_b128 v[204:207], v155 offset:3072
	ds_read_b128 v[208:211], v155 offset:4096
	ds_read_b128 v[212:215], v155 offset:5120
	ds_read_b128 v[216:219], v155 offset:6144
	ds_read_b128 v[220:223], v155 offset:7168
	s_cmp_lg_u32 s98, 0
	s_cbranch_scc1 .Lpi_p9_s
	global_load_lds_dwordx4 v[196:197], off
	v_lshl_add_u64 v[196:197], s[22:23], 0, v[140:141]
	s_add_i32 m0, s21, 0xe000
	s_nop 0
	global_load_lds_dwordx4 v[196:197], off

; #define PG8_STAGE(bufoff, gbase, voff) do { _Pragma("unroll") for (int _i = 0; _i < 2; ++_i) \
;         __builtin_amdgcn_global_load_lds((const unsigned*)((const char*)(gbase) + (voff)[_i]), (LAS unsigned*)(lds + (bufoff) + ldsw + _i * 8192), 16, 0, 0); } while (0)
; #define PG8_LDA(dst, b, h) do { _Pragma("unroll") for (int m = 0; m < 4; ++m) _Pragma("unroll") for (int k = 0; k < 2; ++k) dst[m][k] = *(const LAS bf16x8*)(lds + PG8_SA(b, h) + aoff + m * 2048 + k * 1024); } while (0)
; #define PG8_LDB(dst, b, h) do { _Pragma("unroll") for (int n = 0; n < 2; ++n) _Pragma("unroll") for (int k = 0; k < 2; ++k) dst[n][k] = *(const LAS bf16x8*)(lds + PG8_SB(b, h) + boff + n * 2048 + k * 1024); } while (0)
; #define PG8_SCHED __builtin_amdgcn_sched_barrier(0)
; template <class Epi>
; __device__ __forceinline__ void gemm_phase(LAS unsigned char* lds, const Gemm g, const Sched& S, const Epi& E) {
;     ...
;             PG8_LDB(B0, 1, 0); PG8_LDB(B1, 1, 1); PG8_SCHED; PG8_LDA(At, 1, 0); PG8_STAGE(PG8_SA(0, 1), a2 + hstepA, voffA);
.Lcz_p9_1_j:
	s_setprio 0
	s_barrier
	s_add_i32 s54, 0, 0x18000
	s_add_i32 s55, 0, 0x1c000
	v_add_u32_e32 v168, s54, v147
	v_add_u32_e32 v184, s55, v147
	ds_read_b128 v[156:159], v168
	ds_read_b128 v[160:163], v168 offset:1024
	ds_read_b128 v[164:167], v168 offset:2048
	ds_read_b128 v[168:171], v168 offset:3072
	ds_read_b128 v[172:175], v184
	ds_read_b128 v[176:179], v184 offset:1024
	ds_read_b128 v[180:183], v184 offset:2048
	ds_read_b128 v[184:187], v184 offset:3072
	s_add_u32 s26, s26, 0x40000
	s_addc_u32 s27, s27, 0
	s_mov_b32 m0, s31
	v_lshl_add_u64 v[230:231], s[26:27], 0, v[130:131]
	ds_read_b128 v[188:191], v155 offset:32768
	ds_read_b128 v[192:195], v155 offset:33792
	ds_read_b128 v[200:203], v155 offset:34816
	ds_read_b128 v[204:207], v155 offset:35840
	ds_read_b128 v[208:211], v155 offset:36864
	ds_read_b128 v[212:215], v155 offset:37888
	ds_read_b128 v[216:219], v155 offset:38912
	ds_read_b128 v[220:223], v155 offset:39936
	global_load_lds_dwordx4 v[230:231], off
	v_lshl_add_u64 v[230:231], s[26:27], 0, v[134:135]
	s_mov_b32 m0, s33
	s_nop 0
	global_load_lds_dwordx4 v[230:231], off
	s_cmp_eq_u32 s98, 0
	s_cbranch_scc1 .Lrx_p9_2_n
	s_sub_u32 s98, s98, 1
	s_waitcnt vmcnt(10)
	s_branch .Lrx_p9_2_j

; #define PG8_STAGE(bufoff, gbase, voff) do { _Pragma("unroll") for (int _i = 0; _i < 2; ++_i) \
;         __builtin_amdgcn_global_load_lds((const unsigned*)((const char*)(gbase) + (voff)[_i]), (LAS unsigned*)(lds + (bufoff) + ldsw + _i * 8192), 16, 0, 0); } while (0)
; #define PG8_LDA(dst, b, h) do { _Pragma("unroll") for (int m = 0; m < 4; ++m) _Pragma("unroll") for (int k = 0; k < 2; ++k) dst[m][k] = *(const LAS bf16x8*)(lds + PG8_SA(b, h) + aoff + m * 2048 + k * 1024); } while (0)
; #define PG8_LDB(dst, b, h) do { _Pragma("unroll") for (int n = 0; n < 2; ++n) _Pragma("unroll") for (int k = 0; k < 2; ++k) dst[n][k] = *(const LAS bf16x8*)(lds + PG8_SB(b, h) + boff + n * 2048 + k * 1024); } while (0)
; #define PG8_MMA(ai, bj, At, Bt) do { __builtin_amdgcn_s_setprio(1); _Pragma("unroll") for (int m = 0; m < 4; ++m) _Pragma("unroll") for (int n = 0; n < 2; ++n) _Pragma("unroll") for (int k = 0; k < 2; ++k) \
;         acc[ai][bj][m][n] = __builtin_amdgcn_mfma_f32_16x16x32_bf16(Bt[n][k], At[m][k], acc[ai][bj][m][n], 0, 0, 0); __builtin_amdgcn_s_setprio(0); } while (0)
; #define PG8_WAIT_V(n) asm volatile("s_waitcnt vmcnt(" #n ")" ::: "memory")
; #define PG8_WAIT_L(n) asm volatile("s_waitcnt lgkmcnt(" #n ")" ::: "memory")
; #define PG8_BAR __builtin_amdgcn_s_barrier()
; #define PG8_SCHED __builtin_amdgcn_sched_barrier(0)
; template <class Epi>
; __device__ __forceinline__ void gemm_phase(LAS unsigned char* lds, const Gemm g, const Sched& S, const Epi& E) {
;     ...
;             PG8_LDB(B0, 1, 0); PG8_LDB(B1, 1, 1); PG8_SCHED; PG8_LDA(At, 1, 0); PG8_STAGE(PG8_SA(0, 1), a2 + hstepA, voffA);
;             PG8_WAIT_V(8); PG8_WAIT_L(0); PG8_BAR; PG8_MMA(0, 0, At, B0); PG8_MMA(0, 1, At, B1); PG8_BAR; PG8_SCHED;
;             PG8_LDA(At, 1, 1); PG8_STAGE(PG8_SB(1, 0), b3, voffB); PG8_STAGE(PG8_SB(1, 1), b3 + hstepB, voffB); PG8_STAGE(PG8_SA(1, 0), a3, voffA);
;             PG8_WAIT_V(8); PG8_WAIT_L(0); PG8_BAR; PG8_MMA(1, 0, At, B0); PG8_MMA(1, 1, At, B1); PG8_BAR; PG8_SCHED;
;         }
.Lrx_p9_2_j:
	s_waitcnt lgkmcnt(0)
	s_barrier
	s_setprio 1
	s_waitcnt lgkmcnt(0)
	v_mfma_f32_16x16x32_bf16 v[126:129], v[156:159], v[188:191], v[126:129]
	v_mfma_f32_16x16x32_bf16 v[122:125], v[164:167], v[188:191], v[122:125]
	v_mfma_f32_16x16x32_bf16 v[110:113], v[156:159], v[200:203], v[110:113]
	v_mfma_f32_16x16x32_bf16 v[106:109], v[164:167], v[200:203], v[106:109]
	v_mfma_f32_16x16x32_bf16 v[94:97], v[156:159], v[208:211], v[94:97]
	v_mfma_f32_16x16x32_bf16 v[90:93], v[164:167], v[208:211], v[90:93]
	v_mfma_f32_16x16x32_bf16 v[78:81], v[156:159], v[216:219], v[78:81]
	v_mfma_f32_16x16x32_bf16 v[74:77], v[164:167], v[216:219], v[74:77]
	v_mfma_f32_16x16x32_bf16 v[126:129], v[160:163], v[192:195], v[126:129]
	v_mfma_f32_16x16x32_bf16 v[122:125], v[168:171], v[192:195], v[122:125]
	v_mfma_f32_16x16x32_bf16 v[110:113], v[160:163], v[204:207], v[110:113]
	v_mfma_f32_16x16x32_bf16 v[106:109], v[168:171], v[204:207], v[106:109]
	v_mfma_f32_16x16x32_bf16 v[94:97], v[160:163], v[212:215], v[94:97]
	v_mfma_f32_16x16x32_bf16 v[90:93], v[168:171], v[212:215], v[90:93]
	v_mfma_f32_16x16x32_bf16 v[78:81], v[160:163], v[220:223], v[78:81]
	v_mfma_f32_16x16x32_bf16 v[74:77], v[168:171], v[220:223], v[74:77]
	s_setprio 0
	s_setprio 1
	v_mfma_f32_16x16x32_bf16 v[118:121], v[172:175], v[188:191], v[118:121]
	v_mfma_f32_16x16x32_bf16 v[114:117], v[180:183], v[188:191], v[114:117]
	v_mfma_f32_16x16x32_bf16 v[102:105], v[172:175], v[200:203], v[102:105]
	v_mfma_f32_16x16x32_bf16 v[98:101], v[180:183], v[200:203], v[98:101]
	v_mfma_f32_16x16x32_bf16 v[86:89], v[172:175], v[208:211], v[86:89]
	v_mfma_f32_16x16x32_bf16 v[82:85], v[180:183], v[208:211], v[82:85]
	v_mfma_f32_16x16x32_bf16 v[70:73], v[172:175], v[216:219], v[70:73]
	v_mfma_f32_16x16x32_bf16 v[66:69], v[180:183], v[216:219], v[66:69]
	v_mfma_f32_16x16x32_bf16 v[118:121], v[176:179], v[192:195], v[118:121]
	v_mfma_f32_16x16x32_bf16 v[114:117], v[184:187], v[192:195], v[114:117]
	v_mfma_f32_16x16x32_bf16 v[102:105], v[176:179], v[204:207], v[102:105]
	v_mfma_f32_16x16x32_bf16 v[98:101], v[184:187], v[204:207], v[98:101]
	v_mfma_f32_16x16x32_bf16 v[86:89], v[176:179], v[212:215], v[86:89]
	v_mfma_f32_16x16x32_bf16 v[82:85], v[184:187], v[212:215], v[82:85]
	v_mfma_f32_16x16x32_bf16 v[70:73], v[176:179], v[220:223], v[70:73]
	v_mfma_f32_16x16x32_bf16 v[66:69], v[184:187], v[220:223], v[66:69]
	s_setprio 0
	s_barrier
	s_add_i32 s26, s54, s29
	v_lshl_add_u64 v[196:197], v[196:197], 0, s[6:7]
	s_mov_b32 m0, s26
	ds_read_b128 v[188:191], v155 offset:49152
	ds_read_b128 v[192:195], v155 offset:50176
	ds_read_b128 v[200:203], v155 offset:51200
	ds_read_b128 v[204:207], v155 offset:52224
	ds_read_b128 v[208:211], v155 offset:53248
	ds_read_b128 v[212:215], v155 offset:54272
	ds_read_b128 v[216:219], v155 offset:55296
	ds_read_b128 v[220:223], v155 offset:56320
	global_load_lds_dwordx4 v[196:197], off
	s_add_i32 m0, s26, 0x2000
	s_add_u32 s24, s24, 0x40080
	v_lshl_add_u64 v[196:197], v[224:225], 0, s[6:7]
	s_addc_u32 s25, s25, 0
	s_add_i32 s26, s55, s29
	global_load_lds_dwordx4 v[196:197], off
	v_lshl_add_u64 v[196:197], s[24:25], 0, v[132:133]
	s_mov_b32 m0, s26
	s_nop 0
	global_load_lds_dwordx4 v[196:197], off
	v_lshl_add_u64 v[196:197], s[24:25], 0, v[136:137]
	s_add_i32 m0, s26, 0x2000
	s_nop 0
	global_load_lds_dwordx4 v[196:197], off
	v_lshl_add_u64 v[196:197], v[226:227], 0, s[6:7]
	s_mov_b32 m0, s34
	s_nop 0
	global_load_lds_dwordx4 v[196:197], off
	v_lshl_add_u64 v[196:197], v[228:229], 0, s[6:7]
	s_mov_b32 m0, s35
	s_nop 0
	global_load_lds_dwordx4 v[196:197], off
	s_waitcnt vmcnt(8)
	s_waitcnt lgkmcnt(0)
	s_barrier
	s_setprio 1
	s_waitcnt lgkmcnt(0)
	v_mfma_f32_16x16x32_bf16 v[62:65], v[156:159], v[188:191], v[62:65]
	v_mfma_f32_16x16x32_bf16 v[58:61], v[164:167], v[188:191], v[58:61]
	v_mfma_f32_16x16x32_bf16 v[46:49], v[156:159], v[200:203], v[46:49]
	v_mfma_f32_16x16x32_bf16 v[42:45], v[164:167], v[200:203], v[42:45]
	v_mfma_f32_16x16x32_bf16 v[30:33], v[156:159], v[208:211], v[30:33]
	v_mfma_f32_16x16x32_bf16 v[26:29], v[164:167], v[208:211], v[26:29]
	v_mfma_f32_16x16x32_bf16 v[14:17], v[156:159], v[216:219], v[14:17]
	v_mfma_f32_16x16x32_bf16 v[10:13], v[164:167], v[216:219], v[10:13]
	v_mfma_f32_16x16x32_bf16 v[62:65], v[160:163], v[192:195], v[62:65]
	v_mfma_f32_16x16x32_bf16 v[58:61], v[168:171], v[192:195], v[58:61]
	v_mfma_f32_16x16x32_bf16 v[46:49], v[160:163], v[204:207], v[46:49]
	v_mfma_f32_16x16x32_bf16 v[42:45], v[168:171], v[204:207], v[42:45]
	v_mfma_f32_16x16x32_bf16 v[30:33], v[160:163], v[212:215], v[30:33]
	v_mfma_f32_16x16x32_bf16 v[26:29], v[168:171], v[212:215], v[26:29]
	v_mfma_f32_16x16x32_bf16 v[14:17], v[160:163], v[220:223], v[14:17]
	v_mfma_f32_16x16x32_bf16 v[10:13], v[168:171], v[220:223], v[10:13]
	s_setprio 0
	s_setprio 1
	v_mfma_f32_16x16x32_bf16 v[54:57], v[172:175], v[188:191], v[54:57]
	v_mfma_f32_16x16x32_bf16 v[50:53], v[180:183], v[188:191], v[50:53]
	v_mfma_f32_16x16x32_bf16 v[38:41], v[172:175], v[200:203], v[38:41]
	v_mfma_f32_16x16x32_bf16 v[34:37], v[180:183], v[200:203], v[34:37]
	v_mfma_f32_16x16x32_bf16 v[22:25], v[172:175], v[208:211], v[22:25]
	v_mfma_f32_16x16x32_bf16 v[18:21], v[180:183], v[208:211], v[18:21]
	v_mfma_f32_16x16x32_bf16 v[6:9], v[172:175], v[216:219], v[6:9]
	v_mfma_f32_16x16x32_bf16 v[2:5], v[180:183], v[216:219], v[2:5]
	v_mfma_f32_16x16x32_bf16 v[54:57], v[176:179], v[192:195], v[54:57]
	v_mfma_f32_16x16x32_bf16 v[50:53], v[184:187], v[192:195], v[50:53]
	v_mfma_f32_16x16x32_bf16 v[38:41], v[176:179], v[204:207], v[38:41]
	v_mfma_f32_16x16x32_bf16 v[34:37], v[184:187], v[204:207], v[34:37]
	v_mfma_f32_16x16x32_bf16 v[22:25], v[176:179], v[212:215], v[22:25]
	v_mfma_f32_16x16x32_bf16 v[18:21], v[184:187], v[212:215], v[18:21]
	v_mfma_f32_16x16x32_bf16 v[6:9], v[176:179], v[220:223], v[6:9]
	v_mfma_f32_16x16x32_bf16 v[2:5], v[184:187], v[220:223], v[2:5]
	s_setprio 0
	s_barrier
	s_add_i32 s53, s53, 2
	s_add_u32 s22, s22, 0x100
	s_addc_u32 s23, s23, 0
	s_add_u32 s47, s47, 0x100
	s_addc_u32 s52, s52, 0
	s_cmp_gt_u32 s53, 13
	s_cbranch_scc0 .LBB0_1718
	s_and_b64 vcc, exec, s[8:9]
	s_cbranch_vccz .LBB0_1721
	s_barrier
; #define LAS __attribute__((address_space(3)))
; __device__ __forceinline__ float siluf_(float x) { return x * sigmoidf_(x); }
; __device__ __forceinline__ u32x4 pack8(const f32x4 a, const f32x4 b) { u32x4 w; w.x = cvtpk(a[0], a[1]); w.y = cvtpk(a[2], a[3]); w.z = cvtpk(b[0], b[1]); w.w = cvtpk(b[2], b[3]); return w; }
;     __device__ __forceinline__ void operator()(const Acc& acc, const Unit& u, int wr, int wc, int fr, int fq) const {
;         const int col0 = u.pn * 128 + wc * 32 + 8 * fq;
;         const LAS float* rt = rtab + u.idx * 256 + wr * 64 + fr;
; #pragma unroll
;         for (int ai = 0; ai < 2; ++ai)
; #pragma unroll
;             for (int m = 0; m < 4; ++m) {
;                 const int row = u.pm * BM + ai * HALF + wr * 64 + m * 16 + fr; const float r = rt[ai * HALF + m * 16];
;                 f32x4 h0, h1;
; #pragma unroll
;                 for (int e = 0; e < 4; ++e) { h0[e] = siluf_(acc[ai][0][m][0][e] * r) * (acc[ai][1][m][0][e] * r); h1[e] = siluf_(acc[ai][0][m][1][e] * r) * (acc[ai][1][m][1][e] * r); }
;                 *(u32x4*)(H + (size_t)row * FF + col0) = pack8(h0, h1);
;             }
.LBB0_1721:
	v_lshl_add_u32 v156, s43, 10, v148
	ds_read2_b32 v[158:159], v156 offset1:16
	v_lshl_or_b32 v160, s44, 7, v152
	s_lshl_b32 s11, s20, 8
	v_ashrrev_i32_e32 v161, 31, v160
	s_andn2_b64 vcc, exec, s[0:1]
	s_waitcnt lgkmcnt(0)
	v_pk_mul_f32 v[126:127], v[126:127], v[158:159] op_sel_hi:[1,0]
	v_pk_mul_f32 v[122:123], v[122:123], v[158:159] op_sel_hi:[1,0]
	v_mul_f32_e32 v157, 0xbfb8aa3b, v126
	v_mul_f32_e32 v162, 0xbfb8aa3b, v127
	v_exp_f32_e32 v157, v157
	v_exp_f32_e32 v162, v162
	v_mul_f32_e32 v163, 0xbfb8aa3b, v122
	v_pk_mul_f32 v[118:119], v[118:119], v[158:159] op_sel_hi:[1,0]
	v_add_f32_e32 v157, 1.0, v157
	v_add_f32_e32 v164, 1.0, v162
	v_rcp_f32_e32 v162, v157
	v_exp_f32_e32 v157, v163
	v_mul_f32_e32 v163, 0xbfb8aa3b, v123
	v_exp_f32_e32 v165, v163
	v_rcp_f32_e32 v163, v164
	v_add_f32_e32 v157, 1.0, v157
	v_rcp_f32_e32 v164, v157
	v_add_f32_e32 v157, 1.0, v165
	v_rcp_f32_e32 v165, v157
	v_pk_mul_f32 v[126:127], v[126:127], v[162:163]
	v_pk_mul_f32 v[114:115], v[114:115], v[158:159] op_sel_hi:[1,0]
	v_pk_mul_f32 v[126:127], v[118:119], v[126:127]
	v_pk_mul_f32 v[118:119], v[122:123], v[164:165]
	v_pk_mul_f32 v[122:123], v[128:129], v[158:159] op_sel_hi:[1,0]
	v_pk_mul_f32 v[124:125], v[124:125], v[158:159] op_sel_hi:[1,0]
	v_mul_f32_e32 v128, 0xbfb8aa3b, v122
	v_mul_f32_e32 v129, 0xbfb8aa3b, v123
	v_exp_f32_e32 v128, v128
	v_exp_f32_e32 v129, v129
	v_pk_mul_f32 v[114:115], v[114:115], v[118:119]
	v_pk_mul_f32 v[120:121], v[120:121], v[158:159] op_sel_hi:[1,0]
	v_add_f32_e32 v118, 1.0, v128
	v_add_f32_e32 v119, 1.0, v129
	v_mul_f32_e32 v128, 0xbfb8aa3b, v124
	v_mul_f32_e32 v129, 0xbfb8aa3b, v125
	v_exp_f32_e32 v128, v128
	v_exp_f32_e32 v129, v129
	v_rcp_f32_e32 v118, v118
	v_rcp_f32_e32 v119, v119
	v_add_f32_e32 v128, 1.0, v128
	v_add_f32_e32 v129, 1.0, v129
	v_rcp_f32_e32 v128, v128
	v_rcp_f32_e32 v129, v129
	v_pk_mul_f32 v[118:119], v[122:123], v[118:119]
	v_pk_mul_f32 v[116:117], v[116:117], v[158:159] op_sel_hi:[1,0]
	v_pk_mul_f32 v[122:123], v[120:121], v[118:119]
	v_cvt_pk_bf16_f32 v120, v126, v127
	v_mov_b32_e32 v126, v159
	v_pk_mul_f32 v[110:111], v[110:111], v[126:127] op_sel_hi:[1,0]
	v_pk_mul_f32 v[118:119], v[124:125], v[128:129]
	v_mul_f32_e32 v127, 0xbfb8aa3b, v111
	v_pk_mul_f32 v[116:117], v[116:117], v[118:119]
	v_mul_f32_e32 v119, 0xbfb8aa3b, v110
	v_exp_f32_e32 v127, v127
	v_exp_f32_e32 v119, v119
	v_add_u32_e32 v118, s11, v146
	v_cvt_pk_bf16_f32 v121, v122, v123
	v_cvt_pk_bf16_f32 v122, v114, v115
	v_mov_b64_e32 v[114:115], s[80:81]
	v_cvt_pk_bf16_f32 v123, v116, v117
	v_mad_i64_i32 v[124:125], s[22:23], v118, s38, v[114:115]
	v_lshlrev_b64 v[116:117], 1, v[160:161]
	v_lshl_add_u64 v[124:125], v[124:125], 0, v[116:117]
	v_pk_mul_f32 v[106:107], v[106:107], v[126:127] op_sel_hi:[1,0]
	global_store_dwordx4 v[124:125], v[120:123], off
	v_add_f32_e32 v119, 1.0, v119
	v_pk_mul_f32 v[102:103], v[102:103], v[126:127] op_sel_hi:[1,0]
	v_mul_f32_e32 v121, 0xbfb8aa3b, v106
	v_rcp_f32_e32 v120, v119
	v_add_f32_e32 v119, 1.0, v127
	v_exp_f32_e32 v122, v121
	v_mul_f32_e32 v121, 0xbfb8aa3b, v107
	v_exp_f32_e32 v123, v121
	v_rcp_f32_e32 v121, v119
	v_add_f32_e32 v119, 1.0, v122
	v_rcp_f32_e32 v122, v119
	v_add_f32_e32 v119, 1.0, v123
	v_pk_mul_f32 v[110:111], v[110:111], v[120:121]
	v_rcp_f32_e32 v123, v119
	v_pk_mul_f32 v[102:103], v[102:103], v[110:111]
	v_pk_mul_f32 v[110:111], v[112:113], v[126:127] op_sel_hi:[1,0]
	v_pk_mul_f32 v[98:99], v[98:99], v[126:127] op_sel_hi:[1,0]
	v_mul_f32_e32 v112, 0xbfb8aa3b, v110
	v_mul_f32_e32 v113, 0xbfb8aa3b, v111
	v_exp_f32_e32 v112, v112
	v_exp_f32_e32 v113, v113
	v_pk_mul_f32 v[106:107], v[106:107], v[122:123]
	v_pk_mul_f32 v[108:109], v[108:109], v[126:127] op_sel_hi:[1,0]
	v_pk_mul_f32 v[106:107], v[98:99], v[106:107]
	v_add_f32_e32 v98, 1.0, v112
	v_add_f32_e32 v99, 1.0, v113
	v_mul_f32_e32 v112, 0xbfb8aa3b, v108
	v_mul_f32_e32 v113, 0xbfb8aa3b, v109
	v_exp_f32_e32 v112, v112
	v_exp_f32_e32 v113, v113
	v_rcp_f32_e32 v98, v98
	v_rcp_f32_e32 v99, v99
	v_add_f32_e32 v112, 1.0, v112
	v_add_f32_e32 v113, 1.0, v113
	v_rcp_f32_e32 v112, v112
	v_rcp_f32_e32 v113, v113
	v_pk_mul_f32 v[98:99], v[110:111], v[98:99]
	v_pk_mul_f32 v[104:105], v[104:105], v[126:127] op_sel_hi:[1,0]
	v_pk_mul_f32 v[100:101], v[100:101], v[126:127] op_sel_hi:[1,0]
	v_pk_mul_f32 v[104:105], v[104:105], v[98:99]
	v_pk_mul_f32 v[98:99], v[108:109], v[112:113]
	v_add_u32_e32 v110, s11, v149
	v_pk_mul_f32 v[108:109], v[100:101], v[98:99]
	v_cvt_pk_bf16_f32 v98, v102, v103
	ds_read2_b32 v[102:103], v156 offset0:32 offset1:48
	v_cvt_pk_bf16_f32 v100, v106, v107
	v_cvt_pk_bf16_f32 v99, v104, v105
	v_mad_i64_i32 v[104:105], s[22:23], v110, s38, v[114:115]
	s_waitcnt lgkmcnt(0)
; #define LAS __attribute__((address_space(3)))
; __device__ __forceinline__ float siluf_(float x) { return x * sigmoidf_(x); }
; __device__ __forceinline__ u32x4 pack8(const f32x4 a, const f32x4 b) { u32x4 w; w.x = cvtpk(a[0], a[1]); w.y = cvtpk(a[2], a[3]); w.z = cvtpk(b[0], b[1]); w.w = cvtpk(b[2], b[3]); return w; }
;     __device__ __forceinline__ void operator()(const Acc& acc, const Unit& u, int wr, int wc, int fr, int fq) const {
;         const int col0 = u.pn * 128 + wc * 32 + 8 * fq;
;         const LAS float* rt = rtab + u.idx * 256 + wr * 64 + fr;
; #pragma unroll
;         for (int ai = 0; ai < 2; ++ai)
; #pragma unroll
;             for (int m = 0; m < 4; ++m) {
;                 const int row = u.pm * BM + ai * HALF + wr * 64 + m * 16 + fr; const float r = rt[ai * HALF + m * 16];
;                 f32x4 h0, h1;
; #pragma unroll
;                 for (int e = 0; e < 4; ++e) { h0[e] = siluf_(acc[ai][0][m][0][e] * r) * (acc[ai][1][m][0][e] * r); h1[e] = siluf_(acc[ai][0][m][1][e] * r) * (acc[ai][1][m][1][e] * r); }
;                 *(u32x4*)(H + (size_t)row * FF + col0) = pack8(h0, h1);
;             }
	v_pk_mul_f32 v[94:95], v[94:95], v[102:103] op_sel_hi:[1,0]
	v_cvt_pk_bf16_f32 v101, v108, v109
	v_mul_f32_e32 v106, 0xbfb8aa3b, v94
	v_mul_f32_e32 v107, 0xbfb8aa3b, v95
	v_exp_f32_e32 v106, v106
	v_exp_f32_e32 v107, v107
	v_lshl_add_u64 v[104:105], v[104:105], 0, v[116:117]
	global_store_dwordx4 v[104:105], v[98:101], off
	v_pk_mul_f32 v[90:91], v[90:91], v[102:103] op_sel_hi:[1,0]
	v_pk_mul_f32 v[86:87], v[86:87], v[102:103] op_sel_hi:[1,0]
	v_add_f32_e32 v98, 1.0, v106
	v_add_f32_e32 v99, 1.0, v107
	v_rcp_f32_e32 v98, v98
	v_mul_f32_e32 v100, 0xbfb8aa3b, v90
	v_mul_f32_e32 v101, 0xbfb8aa3b, v91
	v_rcp_f32_e32 v99, v99
	v_exp_f32_e32 v100, v100
	v_exp_f32_e32 v101, v101
	v_pk_mul_f32 v[82:83], v[82:83], v[102:103] op_sel_hi:[1,0]
	v_pk_mul_f32 v[94:95], v[94:95], v[98:99]
	v_add_f32_e32 v100, 1.0, v100
	v_add_f32_e32 v101, 1.0, v101
	v_pk_mul_f32 v[86:87], v[86:87], v[94:95]
	v_pk_mul_f32 v[94:95], v[96:97], v[102:103] op_sel_hi:[1,0]
	v_rcp_f32_e32 v100, v100
	v_rcp_f32_e32 v101, v101
	v_mul_f32_e32 v96, 0xbfb8aa3b, v94
	v_mul_f32_e32 v97, 0xbfb8aa3b, v95
	v_exp_f32_e32 v96, v96
	v_exp_f32_e32 v97, v97
	v_pk_mul_f32 v[90:91], v[90:91], v[100:101]
	v_pk_mul_f32 v[92:93], v[92:93], v[102:103] op_sel_hi:[1,0]
	v_pk_mul_f32 v[90:91], v[82:83], v[90:91]
	v_add_f32_e32 v82, 1.0, v96
	v_add_f32_e32 v83, 1.0, v97
	v_mul_f32_e32 v96, 0xbfb8aa3b, v92
	v_mul_f32_e32 v97, 0xbfb8aa3b, v93
	v_exp_f32_e32 v96, v96
	v_exp_f32_e32 v97, v97
	v_rcp_f32_e32 v82, v82
	v_rcp_f32_e32 v83, v83
	v_add_f32_e32 v96, 1.0, v96
	v_add_f32_e32 v97, 1.0, v97
	v_rcp_f32_e32 v96, v96
	v_rcp_f32_e32 v97, v97
	v_pk_mul_f32 v[82:83], v[94:95], v[82:83]
	v_pk_mul_f32 v[88:89], v[88:89], v[102:103] op_sel_hi:[1,0]
	v_pk_mul_f32 v[84:85], v[84:85], v[102:103] op_sel_hi:[1,0]
	v_pk_mul_f32 v[88:89], v[88:89], v[82:83]
	v_pk_mul_f32 v[82:83], v[92:93], v[96:97]
	v_add_u32_e32 v94, s11, v150
	v_pk_mul_f32 v[92:93], v[84:85], v[82:83]
	v_cvt_pk_bf16_f32 v83, v88, v89
	v_mov_b32_e32 v88, v103
	v_pk_mul_f32 v[78:79], v[78:79], v[88:89] op_sel_hi:[1,0]
	v_cvt_pk_bf16_f32 v84, v90, v91
	v_mul_f32_e32 v89, 0xbfb8aa3b, v78
	v_mul_f32_e32 v90, 0xbfb8aa3b, v79
	v_exp_f32_e32 v89, v89
	v_exp_f32_e32 v90, v90
	v_cvt_pk_bf16_f32 v82, v86, v87
	v_mad_i64_i32 v[86:87], s[22:23], v94, s38, v[114:115]
	v_cvt_pk_bf16_f32 v85, v92, v93
	v_lshl_add_u64 v[86:87], v[86:87], 0, v[116:117]
	global_store_dwordx4 v[86:87], v[82:85], off
	v_pk_mul_f32 v[74:75], v[74:75], v[88:89] op_sel_hi:[1,0]
	v_pk_mul_f32 v[70:71], v[70:71], v[88:89] op_sel_hi:[1,0]
	v_add_f32_e32 v82, 1.0, v89
	v_add_f32_e32 v83, 1.0, v90
	v_rcp_f32_e32 v82, v82
	v_mul_f32_e32 v84, 0xbfb8aa3b, v74
	v_mul_f32_e32 v85, 0xbfb8aa3b, v75
	v_rcp_f32_e32 v83, v83
	v_exp_f32_e32 v84, v84
	v_exp_f32_e32 v85, v85
	v_pk_mul_f32 v[66:67], v[66:67], v[88:89] op_sel_hi:[1,0]
	v_pk_mul_f32 v[78:79], v[78:79], v[82:83]
	v_add_f32_e32 v84, 1.0, v84
	v_add_f32_e32 v85, 1.0, v85
	v_pk_mul_f32 v[70:71], v[70:71], v[78:79]
	v_pk_mul_f32 v[78:79], v[80:81], v[88:89] op_sel_hi:[1,0]
	v_rcp_f32_e32 v84, v84
	v_rcp_f32_e32 v85, v85
	v_mul_f32_e32 v80, 0xbfb8aa3b, v78
	v_mul_f32_e32 v81, 0xbfb8aa3b, v79
	v_exp_f32_e32 v80, v80
	v_exp_f32_e32 v81, v81
	v_pk_mul_f32 v[74:75], v[74:75], v[84:85]
	v_pk_mul_f32 v[76:77], v[76:77], v[88:89] op_sel_hi:[1,0]
	v_pk_mul_f32 v[74:75], v[66:67], v[74:75]
	v_add_f32_e32 v66, 1.0, v80
	v_add_f32_e32 v67, 1.0, v81
	v_mul_f32_e32 v80, 0xbfb8aa3b, v76
	v_mul_f32_e32 v81, 0xbfb8aa3b, v77
	v_exp_f32_e32 v80, v80
	v_exp_f32_e32 v81, v81
	v_rcp_f32_e32 v66, v66
	v_rcp_f32_e32 v67, v67
	v_add_f32_e32 v80, 1.0, v80
	v_add_f32_e32 v81, 1.0, v81
	v_rcp_f32_e32 v80, v80
	v_rcp_f32_e32 v81, v81
	v_pk_mul_f32 v[66:67], v[78:79], v[66:67]
	v_pk_mul_f32 v[72:73], v[72:73], v[88:89] op_sel_hi:[1,0]
	v_pk_mul_f32 v[68:69], v[68:69], v[88:89] op_sel_hi:[1,0]
	v_pk_mul_f32 v[72:73], v[72:73], v[66:67]
	v_pk_mul_f32 v[66:67], v[76:77], v[80:81]
	v_add_u32_e32 v78, s11, v151
	v_pk_mul_f32 v[76:77], v[68:69], v[66:67]
	v_cvt_pk_bf16_f32 v66, v70, v71
	ds_read2_b32 v[70:71], v156 offset0:128 offset1:144
	v_cvt_pk_bf16_f32 v68, v74, v75
	v_cvt_pk_bf16_f32 v67, v72, v73
	v_mad_i64_i32 v[72:73], s[22:23], v78, s38, v[114:115]
	s_waitcnt lgkmcnt(0)
	v_pk_mul_f32 v[62:63], v[62:63], v[70:71] op_sel_hi:[1,0]
	v_cvt_pk_bf16_f32 v69, v76, v77
	v_mul_f32_e32 v74, 0xbfb8aa3b, v62
	v_mul_f32_e32 v75, 0xbfb8aa3b, v63
	v_exp_f32_e32 v74, v74
	v_exp_f32_e32 v75, v75
	v_lshl_add_u64 v[72:73], v[72:73], 0, v[116:117]
	global_store_dwordx4 v[72:73], v[66:69], off
	v_pk_mul_f32 v[58:59], v[58:59], v[70:71] op_sel_hi:[1,0]
	v_pk_mul_f32 v[54:55], v[54:55], v[70:71] op_sel_hi:[1,0]
	v_add_f32_e32 v66, 1.0, v74
	v_add_f32_e32 v67, 1.0, v75
	v_rcp_f32_e32 v66, v66
	v_mul_f32_e32 v68, 0xbfb8aa3b, v58
	v_mul_f32_e32 v69, 0xbfb8aa3b, v59
	v_rcp_f32_e32 v67, v67
	v_exp_f32_e32 v68, v68
	v_exp_f32_e32 v69, v69
	v_pk_mul_f32 v[50:51], v[50:51], v[70:71] op_sel_hi:[1,0]
	v_pk_mul_f32 v[62:63], v[62:63], v[66:67]
	v_add_f32_e32 v68, 1.0, v68
	v_add_f32_e32 v69, 1.0, v69
	v_pk_mul_f32 v[54:55], v[54:55], v[62:63]
	v_pk_mul_f32 v[62:63], v[64:65], v[70:71] op_sel_hi:[1,0]
	v_rcp_f32_e32 v68, v68
	v_rcp_f32_e32 v69, v69
	v_mul_f32_e32 v64, 0xbfb8aa3b, v62
	v_mul_f32_e32 v65, 0xbfb8aa3b, v63
	v_exp_f32_e32 v64, v64
	v_exp_f32_e32 v65, v65
	v_pk_mul_f32 v[58:59], v[58:59], v[68:69]
	v_pk_mul_f32 v[60:61], v[60:61], v[70:71] op_sel_hi:[1,0]
	v_pk_mul_f32 v[58:59], v[50:51], v[58:59]
	v_add_f32_e32 v50, 1.0, v64
	v_add_f32_e32 v51, 1.0, v65
	v_mul_f32_e32 v64, 0xbfb8aa3b, v60
	v_mul_f32_e32 v65, 0xbfb8aa3b, v61
	v_exp_f32_e32 v64, v64
	v_exp_f32_e32 v65, v65
	v_rcp_f32_e32 v50, v50
; #define LAS __attribute__((address_space(3)))
; __device__ __forceinline__ float siluf_(float x) { return x * sigmoidf_(x); }
; __device__ __forceinline__ u32x4 pack8(const f32x4 a, const f32x4 b) { u32x4 w; w.x = cvtpk(a[0], a[1]); w.y = cvtpk(a[2], a[3]); w.z = cvtpk(b[0], b[1]); w.w = cvtpk(b[2], b[3]); return w; }
;     __device__ __forceinline__ void operator()(const Acc& acc, const Unit& u, int wr, int wc, int fr, int fq) const {
;         const int col0 = u.pn * 128 + wc * 32 + 8 * fq;
;         const LAS float* rt = rtab + u.idx * 256 + wr * 64 + fr;
; #pragma unroll
;         for (int ai = 0; ai < 2; ++ai)
; #pragma unroll
;             for (int m = 0; m < 4; ++m) {
;                 const int row = u.pm * BM + ai * HALF + wr * 64 + m * 16 + fr; const float r = rt[ai * HALF + m * 16];
;                 f32x4 h0, h1;
; #pragma unroll
;                 for (int e = 0; e < 4; ++e) { h0[e] = siluf_(acc[ai][0][m][0][e] * r) * (acc[ai][1][m][0][e] * r); h1[e] = siluf_(acc[ai][0][m][1][e] * r) * (acc[ai][1][m][1][e] * r); }
;                 *(u32x4*)(H + (size_t)row * FF + col0) = pack8(h0, h1);
;             }
	v_rcp_f32_e32 v51, v51
	v_add_f32_e32 v64, 1.0, v64
	v_add_f32_e32 v65, 1.0, v65
	v_rcp_f32_e32 v64, v64
	v_rcp_f32_e32 v65, v65
	v_pk_mul_f32 v[50:51], v[62:63], v[50:51]
	v_pk_mul_f32 v[56:57], v[56:57], v[70:71] op_sel_hi:[1,0]
	v_pk_mul_f32 v[52:53], v[52:53], v[70:71] op_sel_hi:[1,0]
	v_pk_mul_f32 v[56:57], v[56:57], v[50:51]
	v_pk_mul_f32 v[50:51], v[60:61], v[64:65]
	v_add_u32_e32 v62, 0x80, v118
	v_pk_mul_f32 v[60:61], v[52:53], v[50:51]
	v_cvt_pk_bf16_f32 v51, v56, v57
	v_mov_b32_e32 v56, v71
	v_pk_mul_f32 v[46:47], v[46:47], v[56:57] op_sel_hi:[1,0]
	v_cvt_pk_bf16_f32 v52, v58, v59
	v_mul_f32_e32 v57, 0xbfb8aa3b, v46
	v_mul_f32_e32 v58, 0xbfb8aa3b, v47
	v_exp_f32_e32 v57, v57
	v_exp_f32_e32 v58, v58
	v_cvt_pk_bf16_f32 v50, v54, v55
	v_mad_i64_i32 v[54:55], s[22:23], v62, s38, v[114:115]
	v_cvt_pk_bf16_f32 v53, v60, v61
	v_lshl_add_u64 v[54:55], v[54:55], 0, v[116:117]
	global_store_dwordx4 v[54:55], v[50:53], off
	v_pk_mul_f32 v[42:43], v[42:43], v[56:57] op_sel_hi:[1,0]
	v_pk_mul_f32 v[38:39], v[38:39], v[56:57] op_sel_hi:[1,0]
	v_add_f32_e32 v50, 1.0, v57
	v_add_f32_e32 v51, 1.0, v58
	v_rcp_f32_e32 v50, v50
	v_mul_f32_e32 v52, 0xbfb8aa3b, v42
	v_mul_f32_e32 v53, 0xbfb8aa3b, v43
	v_rcp_f32_e32 v51, v51
	v_exp_f32_e32 v52, v52
	v_exp_f32_e32 v53, v53
	v_pk_mul_f32 v[34:35], v[34:35], v[56:57] op_sel_hi:[1,0]
	v_pk_mul_f32 v[46:47], v[46:47], v[50:51]
	v_add_f32_e32 v52, 1.0, v52
	v_add_f32_e32 v53, 1.0, v53
	v_pk_mul_f32 v[38:39], v[38:39], v[46:47]
	v_pk_mul_f32 v[46:47], v[48:49], v[56:57] op_sel_hi:[1,0]
	v_rcp_f32_e32 v52, v52
	v_rcp_f32_e32 v53, v53
	v_mul_f32_e32 v48, 0xbfb8aa3b, v46
	v_mul_f32_e32 v49, 0xbfb8aa3b, v47
	v_exp_f32_e32 v48, v48
	v_exp_f32_e32 v49, v49
	v_pk_mul_f32 v[42:43], v[42:43], v[52:53]
	v_pk_mul_f32 v[44:45], v[44:45], v[56:57] op_sel_hi:[1,0]
	v_pk_mul_f32 v[42:43], v[34:35], v[42:43]
	v_add_f32_e32 v34, 1.0, v48
	v_add_f32_e32 v35, 1.0, v49
	v_mul_f32_e32 v48, 0xbfb8aa3b, v44
	v_mul_f32_e32 v49, 0xbfb8aa3b, v45
	v_exp_f32_e32 v48, v48
	v_exp_f32_e32 v49, v49
	v_rcp_f32_e32 v34, v34
	v_rcp_f32_e32 v35, v35
	v_add_f32_e32 v48, 1.0, v48
	v_add_f32_e32 v49, 1.0, v49
	v_rcp_f32_e32 v48, v48
	v_rcp_f32_e32 v49, v49
	v_pk_mul_f32 v[34:35], v[46:47], v[34:35]
	v_pk_mul_f32 v[40:41], v[40:41], v[56:57] op_sel_hi:[1,0]
	v_pk_mul_f32 v[36:37], v[36:37], v[56:57] op_sel_hi:[1,0]
	v_pk_mul_f32 v[40:41], v[40:41], v[34:35]
	v_pk_mul_f32 v[34:35], v[44:45], v[48:49]
	v_add_u32_e32 v46, 0x90, v118
	v_pk_mul_f32 v[44:45], v[36:37], v[34:35]
	v_cvt_pk_bf16_f32 v34, v38, v39
	ds_read2_b32 v[38:39], v156 offset0:160 offset1:176
	v_cvt_pk_bf16_f32 v36, v42, v43
	v_cvt_pk_bf16_f32 v35, v40, v41
	v_mad_i64_i32 v[40:41], s[22:23], v46, s38, v[114:115]
	s_waitcnt lgkmcnt(0)
	v_pk_mul_f32 v[30:31], v[30:31], v[38:39] op_sel_hi:[1,0]
	v_cvt_pk_bf16_f32 v37, v44, v45
	v_mul_f32_e32 v42, 0xbfb8aa3b, v30
	v_mul_f32_e32 v43, 0xbfb8aa3b, v31
	v_exp_f32_e32 v42, v42
	v_exp_f32_e32 v43, v43
	v_lshl_add_u64 v[40:41], v[40:41], 0, v[116:117]
	global_store_dwordx4 v[40:41], v[34:37], off
	s_cbranch_vccnz .Lpi_p9_e
	s_add_u32 s100, s16, 0x40080
	s_addc_u32 s101, s17, 0
	v_lshl_add_u64 v[196:197], s[100:101], 0, v[138:139]
	s_add_i32 m0, s21, 0xc000
	s_nop 0
	global_load_lds_dwordx4 v[196:197], off
	v_lshl_add_u64 v[196:197], s[100:101], 0, v[140:141]
	s_add_i32 m0, s21, 0xe000
	s_nop 0
	global_load_lds_dwordx4 v[196:197], off
; #define LAS __attribute__((address_space(3)))
; __device__ __forceinline__ float siluf_(float x) { return x * sigmoidf_(x); }
; #define PG8_BAR __builtin_amdgcn_s_barrier()
; __device__ __forceinline__ u32x4 pack8(const f32x4 a, const f32x4 b) { u32x4 w; w.x = cvtpk(a[0], a[1]); w.y = cvtpk(a[2], a[3]); w.z = cvtpk(b[0], b[1]); w.w = cvtpk(b[2], b[3]); return w; }
; template <class Epi>
; __device__ __forceinline__ void gemm_phase(LAS unsigned char* lds, const Gemm g, const Sched& S, const Epi& E) {
;     ...
;         if (!has_next) break;
;         if (!(Epi::KEEP_PART0 && cur.part == 0))
; #pragma unroll
;         for (int a = 0; a < 2; ++a)
; #pragma unroll
;             for (int b = 0; b < 2; ++b)
; #pragma unroll
;                 for (int m = 0; m < 4; ++m)
; #pragma unroll
;                     for (int n = 0; n < 2; ++n) acc[a][b][m][n] = (f32x4){0.f, 0.f, 0.f, 0.f};
;         cur = nxt; cA = nA; cB = nB; ++ui;
;         if (wr == 1) PG8_BAR;
;     __device__ __forceinline__ void operator()(const Acc& acc, const Unit& u, int wr, int wc, int fr, int fq) const {
;         const int col0 = u.pn * 128 + wc * 32 + 8 * fq;
;         const LAS float* rt = rtab + u.idx * 256 + wr * 64 + fr;
; #pragma unroll
;         for (int ai = 0; ai < 2; ++ai)
; #pragma unroll
;             for (int m = 0; m < 4; ++m) {
;                 const int row = u.pm * BM + ai * HALF + wr * 64 + m * 16 + fr; const float r = rt[ai * HALF + m * 16];
;                 f32x4 h0, h1;
; #pragma unroll
;                 for (int e = 0; e < 4; ++e) { h0[e] = siluf_(acc[ai][0][m][0][e] * r) * (acc[ai][1][m][0][e] * r); h1[e] = siluf_(acc[ai][0][m][1][e] * r) * (acc[ai][1][m][1][e] * r); }
;                 *(u32x4*)(H + (size_t)row * FF + col0) = pack8(h0, h1);
;             }
.Lpi_p9_e:
	v_pk_mul_f32 v[26:27], v[26:27], v[38:39] op_sel_hi:[1,0]
	v_pk_mul_f32 v[22:23], v[22:23], v[38:39] op_sel_hi:[1,0]
	v_add_f32_e32 v34, 1.0, v42
	v_add_f32_e32 v35, 1.0, v43
	v_rcp_f32_e32 v34, v34
	v_mul_f32_e32 v36, 0xbfb8aa3b, v26
	v_mul_f32_e32 v37, 0xbfb8aa3b, v27
	v_rcp_f32_e32 v35, v35
	v_exp_f32_e32 v36, v36
	v_exp_f32_e32 v37, v37
	v_pk_mul_f32 v[18:19], v[18:19], v[38:39] op_sel_hi:[1,0]
	v_pk_mul_f32 v[30:31], v[30:31], v[34:35]
	v_add_f32_e32 v36, 1.0, v36
	v_add_f32_e32 v37, 1.0, v37
	v_pk_mul_f32 v[22:23], v[22:23], v[30:31]
	v_pk_mul_f32 v[30:31], v[32:33], v[38:39] op_sel_hi:[1,0]
	v_rcp_f32_e32 v36, v36
	v_rcp_f32_e32 v37, v37
	v_mul_f32_e32 v32, 0xbfb8aa3b, v30
	v_mul_f32_e32 v33, 0xbfb8aa3b, v31
	v_exp_f32_e32 v32, v32
	v_exp_f32_e32 v33, v33
	v_pk_mul_f32 v[26:27], v[26:27], v[36:37]
	v_pk_mul_f32 v[28:29], v[28:29], v[38:39] op_sel_hi:[1,0]
	v_pk_mul_f32 v[26:27], v[18:19], v[26:27]
	v_add_f32_e32 v18, 1.0, v32
	v_add_f32_e32 v19, 1.0, v33
	v_mul_f32_e32 v32, 0xbfb8aa3b, v28
	v_mul_f32_e32 v33, 0xbfb8aa3b, v29
	v_exp_f32_e32 v32, v32
	v_exp_f32_e32 v33, v33
	v_rcp_f32_e32 v18, v18
	v_rcp_f32_e32 v19, v19
	v_add_f32_e32 v32, 1.0, v32
	v_add_f32_e32 v33, 1.0, v33
	v_rcp_f32_e32 v32, v32
	v_rcp_f32_e32 v33, v33
	v_pk_mul_f32 v[18:19], v[30:31], v[18:19]
	v_pk_mul_f32 v[24:25], v[24:25], v[38:39] op_sel_hi:[1,0]
	v_pk_mul_f32 v[20:21], v[20:21], v[38:39] op_sel_hi:[1,0]
	v_pk_mul_f32 v[24:25], v[24:25], v[18:19]
	v_pk_mul_f32 v[18:19], v[28:29], v[32:33]
	v_add_u32_e32 v30, 0xa0, v118
	v_pk_mul_f32 v[28:29], v[20:21], v[18:19]
	v_cvt_pk_bf16_f32 v19, v24, v25
	v_mov_b32_e32 v24, v39
	v_pk_mul_f32 v[14:15], v[14:15], v[24:25] op_sel_hi:[1,0]
	v_cvt_pk_bf16_f32 v20, v26, v27
	v_mul_f32_e32 v25, 0xbfb8aa3b, v14
	v_mul_f32_e32 v26, 0xbfb8aa3b, v15
	v_exp_f32_e32 v25, v25
	v_exp_f32_e32 v26, v26
	v_cvt_pk_bf16_f32 v18, v22, v23
	v_mad_i64_i32 v[22:23], s[22:23], v30, s38, v[114:115]
	v_cvt_pk_bf16_f32 v21, v28, v29
	v_lshl_add_u64 v[22:23], v[22:23], 0, v[116:117]
	global_store_dwordx4 v[22:23], v[18:21], off
	v_pk_mul_f32 v[10:11], v[10:11], v[24:25] op_sel_hi:[1,0]
	v_pk_mul_f32 v[6:7], v[6:7], v[24:25] op_sel_hi:[1,0]
	v_add_f32_e32 v18, 1.0, v25
	v_add_f32_e32 v19, 1.0, v26
	v_rcp_f32_e32 v18, v18
	v_mul_f32_e32 v20, 0xbfb8aa3b, v10
	v_mul_f32_e32 v21, 0xbfb8aa3b, v11
	v_rcp_f32_e32 v19, v19
	v_exp_f32_e32 v20, v20
	v_exp_f32_e32 v21, v21
	v_pk_mul_f32 v[2:3], v[2:3], v[24:25] op_sel_hi:[1,0]
	v_pk_mul_f32 v[14:15], v[14:15], v[18:19]
	v_add_f32_e32 v20, 1.0, v20
	v_add_f32_e32 v21, 1.0, v21
	v_pk_mul_f32 v[6:7], v[6:7], v[14:15]
	v_pk_mul_f32 v[14:15], v[16:17], v[24:25] op_sel_hi:[1,0]
	v_rcp_f32_e32 v20, v20
	v_rcp_f32_e32 v21, v21
	v_mul_f32_e32 v16, 0xbfb8aa3b, v14
	v_mul_f32_e32 v17, 0xbfb8aa3b, v15
	v_exp_f32_e32 v16, v16
	v_exp_f32_e32 v17, v17
	v_pk_mul_f32 v[10:11], v[10:11], v[20:21]
	v_pk_mul_f32 v[12:13], v[12:13], v[24:25] op_sel_hi:[1,0]
	v_pk_mul_f32 v[10:11], v[2:3], v[10:11]
	v_add_f32_e32 v2, 1.0, v16
	v_add_f32_e32 v3, 1.0, v17
	v_mul_f32_e32 v16, 0xbfb8aa3b, v12
	v_mul_f32_e32 v17, 0xbfb8aa3b, v13
	v_exp_f32_e32 v16, v16
	v_exp_f32_e32 v17, v17
	v_rcp_f32_e32 v2, v2
	v_rcp_f32_e32 v3, v3
	v_add_f32_e32 v16, 1.0, v16
	v_add_f32_e32 v17, 1.0, v17
	v_rcp_f32_e32 v16, v16
	v_rcp_f32_e32 v17, v17
	v_pk_mul_f32 v[2:3], v[14:15], v[2:3]
	v_pk_mul_f32 v[8:9], v[8:9], v[24:25] op_sel_hi:[1,0]
	v_pk_mul_f32 v[4:5], v[4:5], v[24:25] op_sel_hi:[1,0]
	v_pk_mul_f32 v[8:9], v[8:9], v[2:3]
	v_pk_mul_f32 v[2:3], v[12:13], v[16:17]
	v_add_u32_e32 v14, 0xb0, v118
	v_pk_mul_f32 v[12:13], v[4:5], v[2:3]
	v_cvt_pk_bf16_f32 v2, v6, v7
	v_mad_i64_i32 v[6:7], s[22:23], v14, s38, v[114:115]
	v_cvt_pk_bf16_f32 v3, v8, v9
	v_cvt_pk_bf16_f32 v4, v10, v11
	v_cvt_pk_bf16_f32 v5, v12, v13
	v_lshl_add_u64 v[6:7], v[6:7], 0, v[116:117]
	s_mov_b64 s[0:1], -1
	global_store_dwordx4 v[6:7], v[2:5], off
	s_cbranch_vccnz .LBB0_1710
	s_andn2_b64 vcc, exec, s[4:5]
	s_cbranch_vccnz .LBB0_1709
	s_barrier
	s_branch .LBB0_1709
